# W2GU share of the P3 idle-slot conversion (1536 items) also moved to idle waves at seams 2-4, P3 slot shortened
# baseline (speedup 1.0000x reference)
; __device__ __forceinline__ TrItem tr_decode(int it, const float* const* in, unsigned char* ws, int lane) {
;     int r = it, kind = 0, ndb = 32, N = D, K = D; const float *W, *W2 = nullptr, *gain = nullptr; bf16_t* WT; bool nts = false, woh = false;
;     if (r < 5632) { kind = 1; W = in[3]; W2 = in[4]; N = FF; ndb = 176; gain = in[2]; WT = (bf16_t*)(ws + WS_W1GU); }
;     else if ((r -= 5632) < 2816) { W = in[5]; K = FF; WT = (bf16_t*)(ws + WS_W1D); }
;     else if ((r -= 2816) < 2688) { kind = 2; W = in[7]; N = INC; ndb = 84; gain = in[6]; WT = (bf16_t*)(ws + WS_WIN); nts = true; }
;     else if ((r -= 2688) < 1024) { W = in[10]; WT = (bf16_t*)(ws + WS_WOUT); nts = true; }
;     else if ((r -= 1024) < 1024) { W = in[13]; gain = in[11]; WT = (bf16_t*)(ws + WS_WQ); nts = true; }
;     else if ((r -= 1024) < 2048) { W = in[14]; N = 2 * D; ndb = 64; gain = in[12]; WT = (bf16_t*)(ws + WS_WKV); }
;     else if ((r -= 2048) < 1024) { W = in[15]; WT = (bf16_t*)(ws + WS_WO); nts = true; woh = true; }
;     else if ((r -= 1024) < 5632) { kind = 1; W = in[17]; W2 = in[18]; N = FF; ndb = 176; gain = in[16]; WT = (bf16_t*)(ws + WS_W2GU); nts = true; }
;     else { r -= 5632; W = in[19]; K = FF; WT = (bf16_t*)(ws + WS_W2D); }
;     ...
;     constexpr int KL = TR_ORDER, DL = 3 - TR_ORDER;
;     const int rh = r >> 3, rl = r & 7, nq = ndb >> DL, kbh = rh / nq, dbh = rh - kbh * nq;
;     const int kb = (kbh << KL) + (rl >> DL), db = (dbh << DL) + (rl & ((1 << DL) - 1)), d0 = db * 64, k0 = kb * 64;
;     ...
;     const int kb = r / ndb, db = r - kb * ndb, d0 = db * 64, k0 = kb * 64;
;     ...
;     const int blk = d0 + 32 * ((lane & 15) >> 3);
;     const float* src = W; int s0 = blk;
;     if (kind == 1) { const int pn = blk >> 8, bj = (blk >> 7) & 1, o = blk & 127; src = bj ? W2 : W; s0 = pn * 128 + o; }
;     else if (kind == 2) s0 = win_src(blk);
;     TrItem t; t.src = src + (size_t)(k0 + (lane >> 4)) * N + s0 + 4 * (lane & 7); t.gain = gain ? gain + k0 + 8 * (lane & 7) : nullptr;
;     t.dst = WT + (size_t)(d0 + (lane >> 3)) * K + k0 + 8 * (lane & 7); t.N = N; t.K = K; t.nts = nts && TR_NTS;
; __device__ __forceinline__ void tr_all(const float* const* in, unsigned char* ws, LAS float* scr, int gw, int ngw, int lane, const TrRanges rg) {
;     ...
;     for (int i = 0; i < 16; ++i) v[i] = TR_LOAD((const f32x4*)(cur.src + (size_t)(4 * i) * cur.N));
;     for (int it = gw; it < TR_CNT; it += ngw) {
.Lseam_cv_2_1:
	s_cmp_gt_u32 s98, 7
	s_cbranch_scc1 .LBB0_681
	s_mov_b64 exec, -1
	s_lshl_b32 s99, s87, 1
	s_add_i32 s99, s99, s98
	s_add_i32 s99, s99, 0xfffffffa
	s_lshr_b32 s100, s99, 3
	s_mul_i32 s101, s100, 0x5d2
	s_lshr_b32 s101, s101, 16
	s_mul_i32 vcc_lo, s101, 44
	s_sub_i32 s100, s100, vcc_lo
	s_and_b32 vcc_lo, s99, 7
	s_lshr_b32 vcc_hi, vcc_lo, 2
	s_lshl_b32 s101, s101, 1
	s_add_i32 s101, s101, vcc_hi
	s_and_b32 vcc_lo, vcc_lo, 3
	s_lshl_b32 s100, s100, 2
	s_add_i32 s100, s100, vcc_lo
	s_lshl_b32 s101, s101, 6
	s_lshl_b32 s100, s100, 6
	v_and_b32_e32 v66, 63, v1
	v_lshrrev_b32_e32 v67, 4, v66
	v_and_b32_e32 v68, 15, v66
	v_and_b32_e32 v73, 7, v66
	v_lshrrev_b32_e32 v72, 3, v66
	s_mul_i32 s99, s98, 0x4100
	v_mul_u32_u24_e32 v70, 0x104, v67
	v_lshl_add_u32 v70, v68, 4, v70
	v_add_u32_e32 v70, s99, v70
	v_mul_u32_u24_e32 v71, 0x820, v73
	v_lshl_add_u32 v71, v72, 2, v71
	v_add_u32_e32 v71, s99, v71
	s_mul_i32 s99, s101, 0x1600
	s_lshr_b32 vcc_lo, s100, 8
	s_lshl_b32 vcc_lo, vcc_lo, 7
	s_add_i32 s99, s99, vcc_lo
	s_and_b32 vcc_lo, s100, 0x7f
	s_add_i32 s99, s99, vcc_lo
	s_lshl_b32 s99, s99, 2
	v_mul_u32_u24_e32 v69, 0x5800, v67
	v_lshl_add_u32 v69, v68, 4, v69
	v_add_u32_e32 v69, s99, v69
	s_lshl_b32 s99, s100, 12
	s_lshl_b32 vcc_lo, s101, 1
	s_add_i32 s99, s99, vcc_lo
	v_lshlrev_b32_e32 v72, 12, v72
	v_lshl_add_u32 v72, v73, 4, v72
	v_add_u32_e32 v72, s99, v72
	s_lshl_b32 s99, s101, 2
	v_lshlrev_b32_e32 v73, 5, v73
	v_add_u32_e32 v73, s99, v73
	s_nop 0
	s_bitcmp1_b32 s100, 7
	v_readlane_b32 s100, v254, 6
	v_readlane_b32 s101, v254, 7
	v_readlane_b32 s98, v254, 8
	v_readlane_b32 s99, v254, 9
	s_nop 3
	s_cselect_b32 s100, s98, s100
	s_cselect_b32 s101, s99, s101
	v_readlane_b32 s98, v254, 4
	v_readlane_b32 s99, v254, 5
	global_load_dwordx4 v[2:5], v69, s[100:101] nt
	v_add_u32_e32 v68, 0x16000, v69
	global_load_dwordx4 v[6:9], v68, s[100:101] nt
	v_add_u32_e32 v67, 0x2c000, v69
	global_load_dwordx4 v[10:13], v67, s[100:101] nt
	v_add_u32_e32 v68, 0x42000, v69
	global_load_dwordx4 v[14:17], v68, s[100:101] nt
	v_add_u32_e32 v67, 0x58000, v69
	global_load_dwordx4 v[18:21], v67, s[100:101] nt
	v_add_u32_e32 v68, 0x6e000, v69
	global_load_dwordx4 v[22:25], v68, s[100:101] nt
	v_add_u32_e32 v67, 0x84000, v69
	global_load_dwordx4 v[26:29], v67, s[100:101] nt
	v_add_u32_e32 v68, 0x9a000, v69
	global_load_dwordx4 v[30:33], v68, s[100:101] nt
	v_add_u32_e32 v67, 0xb0000, v69
	global_load_dwordx4 v[34:37], v67, s[100:101] nt
	v_add_u32_e32 v68, 0xc6000, v69
	global_load_dwordx4 v[38:41], v68, s[100:101] nt
	v_add_u32_e32 v67, 0xdc000, v69
	global_load_dwordx4 v[42:45], v67, s[100:101] nt
	v_add_u32_e32 v68, 0xf2000, v69
	global_load_dwordx4 v[46:49], v68, s[100:101] nt
	v_add_u32_e32 v67, 0x108000, v69
	global_load_dwordx4 v[50:53], v67, s[100:101] nt
	v_add_u32_e32 v68, 0x11e000, v69
	global_load_dwordx4 v[54:57], v68, s[100:101] nt
	v_add_u32_e32 v67, 0x134000, v69
	global_load_dwordx4 v[58:61], v67, s[100:101] nt
	v_add_u32_e32 v68, 0x14a000, v69
	global_load_dwordx4 v[62:65], v68, s[100:101] nt
	global_load_dwordx4 v[74:77], v73, s[98:99]
	global_load_dwordx4 v[78:81], v73, s[98:99] offset:16
	s_waitcnt vmcnt(17)
	ds_write_b32 v70, v2
	ds_write_b32 v70, v3 offset:4
	ds_write_b32 v70, v4 offset:8
	ds_write_b32 v70, v5 offset:12
	s_waitcnt vmcnt(16)
	ds_write_b32 v70, v6 offset:1040
	ds_write_b32 v70, v7 offset:1044
	ds_write_b32 v70, v8 offset:1048
	ds_write_b32 v70, v9 offset:1052
	s_waitcnt vmcnt(15)
	ds_write_b32 v70, v10 offset:2080
	ds_write_b32 v70, v11 offset:2084
	ds_write_b32 v70, v12 offset:2088
	ds_write_b32 v70, v13 offset:2092
	s_waitcnt vmcnt(14)
	ds_write_b32 v70, v14 offset:3120
	ds_write_b32 v70, v15 offset:3124
	ds_write_b32 v70, v16 offset:3128
	ds_write_b32 v70, v17 offset:3132
	s_waitcnt vmcnt(13)
	ds_write_b32 v70, v18 offset:4160
	ds_write_b32 v70, v19 offset:4164
	ds_write_b32 v70, v20 offset:4168
	ds_write_b32 v70, v21 offset:4172
	s_waitcnt vmcnt(12)
	ds_write_b32 v70, v22 offset:5200
	ds_write_b32 v70, v23 offset:5204
	ds_write_b32 v70, v24 offset:5208
	ds_write_b32 v70, v25 offset:5212
	s_waitcnt vmcnt(11)
	ds_write_b32 v70, v26 offset:6240
	ds_write_b32 v70, v27 offset:6244
	ds_write_b32 v70, v28 offset:6248
	ds_write_b32 v70, v29 offset:6252
	s_waitcnt vmcnt(10)
	ds_write_b32 v70, v30 offset:7280
	ds_write_b32 v70, v31 offset:7284
	ds_write_b32 v70, v32 offset:7288
	ds_write_b32 v70, v33 offset:7292
	s_waitcnt vmcnt(9)
	ds_write_b32 v70, v34 offset:8320
	ds_write_b32 v70, v35 offset:8324
	ds_write_b32 v70, v36 offset:8328
	ds_write_b32 v70, v37 offset:8332
	s_waitcnt vmcnt(8)
	ds_write_b32 v70, v38 offset:9360
	ds_write_b32 v70, v39 offset:9364
	ds_write_b32 v70, v40 offset:9368
	ds_write_b32 v70, v41 offset:9372
	s_waitcnt vmcnt(7)
	ds_write_b32 v70, v42 offset:10400
	ds_write_b32 v70, v43 offset:10404
	ds_write_b32 v70, v44 offset:10408
	ds_write_b32 v70, v45 offset:10412
	s_waitcnt vmcnt(6)
	ds_write_b32 v70, v46 offset:11440
	ds_write_b32 v70, v47 offset:11444
	ds_write_b32 v70, v48 offset:11448
	ds_write_b32 v70, v49 offset:11452
	s_waitcnt vmcnt(5)
	ds_write_b32 v70, v50 offset:12480
	ds_write_b32 v70, v51 offset:12484
	ds_write_b32 v70, v52 offset:12488
	ds_write_b32 v70, v53 offset:12492
	s_waitcnt vmcnt(4)
	ds_write_b32 v70, v54 offset:13520
	ds_write_b32 v70, v55 offset:13524
	ds_write_b32 v70, v56 offset:13528
	ds_write_b32 v70, v57 offset:13532
	s_waitcnt vmcnt(3)
	ds_write_b32 v70, v58 offset:14560
	ds_write_b32 v70, v59 offset:14564
	ds_write_b32 v70, v60 offset:14568
	ds_write_b32 v70, v61 offset:14572
	s_waitcnt vmcnt(2)
; #define LAS __attribute__((address_space(3)))
; __device__ __forceinline__ unsigned cvtpk(float lo, float hi) { f32x2_t v = {lo, hi}; bf16x2_t b = __builtin_convertvector(v, bf16x2_t); return __builtin_bit_cast(unsigned, b); }
; __device__ __forceinline__ void tr_all(const float* const* in, unsigned char* ws, LAS float* scr, int gw, int ngw, int lane, const TrRanges rg) {
;     ...
;         const LAS float* rp = scr + (8 * (lane & 7)) * 65 + (lane >> 3);
; #pragma unroll
;         for (int j = 0; j < 8; ++j) { const LAS float* s = rp + 8 * j;
;             u32x4 o; o.x = cvtpk(s[0 * 65] * g0[0], s[1 * 65] * g0[1]); o.y = cvtpk(s[2 * 65] * g0[2], s[3 * 65] * g0[3]);
;             o.z = cvtpk(s[4 * 65] * g1[0], s[5 * 65] * g1[1]); o.w = cvtpk(s[6 * 65] * g1[2], s[7 * 65] * g1[3]);
;             if (cur.nts) __builtin_nontemporal_store(o, (u32x4*)(cur.dst + (size_t)(8 * j) * cur.K)); else *(u32x4*)(cur.dst + (size_t)(8 * j) * cur.K) = o; }
;         asm volatile("s_waitcnt lgkmcnt(0)" ::: "memory");
	ds_write_b32 v70, v62 offset:15600
	ds_write_b32 v70, v63 offset:15604
	ds_write_b32 v70, v64 offset:15608
	ds_write_b32 v70, v65 offset:15612
	s_add_u32 s100, s84, 0x8f00000
	s_addc_u32 s101, s85, 0
	s_waitcnt vmcnt(0) lgkmcnt(0)
	ds_read_b32 v2, v71
	ds_read_b32 v3, v71 offset:260
	ds_read_b32 v4, v71 offset:520
	ds_read_b32 v5, v71 offset:780
	ds_read_b32 v6, v71 offset:1040
	ds_read_b32 v7, v71 offset:1300
	ds_read_b32 v8, v71 offset:1560
	ds_read_b32 v9, v71 offset:1820
	ds_read_b32 v10, v71 offset:32
	ds_read_b32 v11, v71 offset:292
	ds_read_b32 v12, v71 offset:552
	ds_read_b32 v13, v71 offset:812
	ds_read_b32 v14, v71 offset:1072
	ds_read_b32 v15, v71 offset:1332
	ds_read_b32 v16, v71 offset:1592
	ds_read_b32 v17, v71 offset:1852
	ds_read_b32 v18, v71 offset:64
	ds_read_b32 v19, v71 offset:324
	ds_read_b32 v20, v71 offset:584
	ds_read_b32 v21, v71 offset:844
	ds_read_b32 v22, v71 offset:1104
	ds_read_b32 v23, v71 offset:1364
	ds_read_b32 v24, v71 offset:1624
	ds_read_b32 v25, v71 offset:1884
	ds_read_b32 v26, v71 offset:96
	ds_read_b32 v27, v71 offset:356
	ds_read_b32 v28, v71 offset:616
	ds_read_b32 v29, v71 offset:876
	ds_read_b32 v30, v71 offset:1136
	ds_read_b32 v31, v71 offset:1396
	ds_read_b32 v32, v71 offset:1656
	ds_read_b32 v33, v71 offset:1916
	ds_read_b32 v34, v71 offset:128
	ds_read_b32 v35, v71 offset:388
	ds_read_b32 v36, v71 offset:648
	ds_read_b32 v37, v71 offset:908
	ds_read_b32 v38, v71 offset:1168
	ds_read_b32 v39, v71 offset:1428
	ds_read_b32 v40, v71 offset:1688
	ds_read_b32 v41, v71 offset:1948
	ds_read_b32 v42, v71 offset:160
	ds_read_b32 v43, v71 offset:420
	ds_read_b32 v44, v71 offset:680
	ds_read_b32 v45, v71 offset:940
	ds_read_b32 v46, v71 offset:1200
	ds_read_b32 v47, v71 offset:1460
	ds_read_b32 v48, v71 offset:1720
	ds_read_b32 v49, v71 offset:1980
	ds_read_b32 v50, v71 offset:192
	ds_read_b32 v51, v71 offset:452
	ds_read_b32 v52, v71 offset:712
	ds_read_b32 v53, v71 offset:972
	ds_read_b32 v54, v71 offset:1232
	ds_read_b32 v55, v71 offset:1492
	ds_read_b32 v56, v71 offset:1752
	ds_read_b32 v57, v71 offset:2012
	ds_read_b32 v58, v71 offset:224
	ds_read_b32 v59, v71 offset:484
	ds_read_b32 v60, v71 offset:744
	ds_read_b32 v61, v71 offset:1004
	ds_read_b32 v62, v71 offset:1264
	ds_read_b32 v63, v71 offset:1524
	ds_read_b32 v64, v71 offset:1784
	ds_read_b32 v65, v71 offset:2044
	s_waitcnt lgkmcnt(15)
	v_mul_f32_e32 v2, v2, v74
	v_mul_f32_e32 v3, v3, v75
	v_mul_f32_e32 v4, v4, v76
	v_mul_f32_e32 v5, v5, v77
	v_mul_f32_e32 v6, v6, v78
	v_mul_f32_e32 v7, v7, v79
	v_mul_f32_e32 v8, v8, v80
	v_mul_f32_e32 v9, v9, v81
	v_cvt_pk_bf16_f32 v192, v2, v3
	v_cvt_pk_bf16_f32 v193, v4, v5
	v_cvt_pk_bf16_f32 v194, v6, v7
	v_cvt_pk_bf16_f32 v195, v8, v9
	global_store_dwordx4 v72, v[192:195], s[100:101] nt
	s_waitcnt lgkmcnt(15)
	v_mul_f32_e32 v10, v10, v74
	v_mul_f32_e32 v11, v11, v75
	v_mul_f32_e32 v12, v12, v76
	v_mul_f32_e32 v13, v13, v77
	v_mul_f32_e32 v14, v14, v78
	v_mul_f32_e32 v15, v15, v79
	v_mul_f32_e32 v16, v16, v80
	v_mul_f32_e32 v17, v17, v81
	v_cvt_pk_bf16_f32 v196, v10, v11
	v_cvt_pk_bf16_f32 v197, v12, v13
	v_cvt_pk_bf16_f32 v198, v14, v15
	v_cvt_pk_bf16_f32 v199, v16, v17
	v_add_u32_e32 v68, 0x8000, v72
	global_store_dwordx4 v68, v[196:199], s[100:101] nt
	s_waitcnt lgkmcnt(15)
	v_mul_f32_e32 v18, v18, v74
	v_mul_f32_e32 v19, v19, v75
	v_mul_f32_e32 v20, v20, v76
	v_mul_f32_e32 v21, v21, v77
	v_mul_f32_e32 v22, v22, v78
	v_mul_f32_e32 v23, v23, v79
	v_mul_f32_e32 v24, v24, v80
	v_mul_f32_e32 v25, v25, v81
	v_cvt_pk_bf16_f32 v200, v18, v19
	v_cvt_pk_bf16_f32 v201, v20, v21
	v_cvt_pk_bf16_f32 v202, v22, v23
	v_cvt_pk_bf16_f32 v203, v24, v25
	v_add_u32_e32 v67, 0x10000, v72
	global_store_dwordx4 v67, v[200:203], s[100:101] nt
	s_waitcnt lgkmcnt(15)
	v_mul_f32_e32 v26, v26, v74
	v_mul_f32_e32 v27, v27, v75
	v_mul_f32_e32 v28, v28, v76
	v_mul_f32_e32 v29, v29, v77
	v_mul_f32_e32 v30, v30, v78
	v_mul_f32_e32 v31, v31, v79
	v_mul_f32_e32 v32, v32, v80
	v_mul_f32_e32 v33, v33, v81
	v_cvt_pk_bf16_f32 v204, v26, v27
	v_cvt_pk_bf16_f32 v205, v28, v29
	v_cvt_pk_bf16_f32 v206, v30, v31
	v_cvt_pk_bf16_f32 v207, v32, v33
	v_add_u32_e32 v68, 0x18000, v72
	global_store_dwordx4 v68, v[204:207], s[100:101] nt
	s_waitcnt lgkmcnt(15)
	v_mul_f32_e32 v34, v34, v74
	v_mul_f32_e32 v35, v35, v75
	v_mul_f32_e32 v36, v36, v76
	v_mul_f32_e32 v37, v37, v77
	v_mul_f32_e32 v38, v38, v78
	v_mul_f32_e32 v39, v39, v79
	v_mul_f32_e32 v40, v40, v80
	v_mul_f32_e32 v41, v41, v81
	v_cvt_pk_bf16_f32 v208, v34, v35
	v_cvt_pk_bf16_f32 v209, v36, v37
	v_cvt_pk_bf16_f32 v210, v38, v39
	v_cvt_pk_bf16_f32 v211, v40, v41
	v_add_u32_e32 v67, 0x20000, v72
	global_store_dwordx4 v67, v[208:211], s[100:101] nt
	s_waitcnt lgkmcnt(15)
	v_mul_f32_e32 v42, v42, v74
	v_mul_f32_e32 v43, v43, v75
	v_mul_f32_e32 v44, v44, v76
	v_mul_f32_e32 v45, v45, v77
	v_mul_f32_e32 v46, v46, v78
	v_mul_f32_e32 v47, v47, v79
	v_mul_f32_e32 v48, v48, v80
	v_mul_f32_e32 v49, v49, v81
	v_cvt_pk_bf16_f32 v212, v42, v43
	v_cvt_pk_bf16_f32 v213, v44, v45
	v_cvt_pk_bf16_f32 v214, v46, v47
	v_cvt_pk_bf16_f32 v215, v48, v49
	v_add_u32_e32 v68, 0x28000, v72
	global_store_dwordx4 v68, v[212:215], s[100:101] nt
	s_waitcnt lgkmcnt(8)
	v_mul_f32_e32 v50, v50, v74
	v_mul_f32_e32 v51, v51, v75
	v_mul_f32_e32 v52, v52, v76
	v_mul_f32_e32 v53, v53, v77
	v_mul_f32_e32 v54, v54, v78
	v_mul_f32_e32 v55, v55, v79
	v_mul_f32_e32 v56, v56, v80
	v_mul_f32_e32 v57, v57, v81
	v_cvt_pk_bf16_f32 v216, v50, v51
	v_cvt_pk_bf16_f32 v217, v52, v53
	v_cvt_pk_bf16_f32 v218, v54, v55
	v_cvt_pk_bf16_f32 v219, v56, v57
	v_add_u32_e32 v67, 0x30000, v72
	global_store_dwordx4 v67, v[216:219], s[100:101] nt
	s_waitcnt lgkmcnt(0)
	v_mul_f32_e32 v58, v58, v74
	v_mul_f32_e32 v59, v59, v75
	v_mul_f32_e32 v60, v60, v76
	v_mul_f32_e32 v61, v61, v77
	v_mul_f32_e32 v62, v62, v78
	v_mul_f32_e32 v63, v63, v79
	v_mul_f32_e32 v64, v64, v80
	v_mul_f32_e32 v65, v65, v81
	v_cvt_pk_bf16_f32 v220, v58, v59
	v_cvt_pk_bf16_f32 v221, v60, v61
	v_cvt_pk_bf16_f32 v222, v62, v63
	v_cvt_pk_bf16_f32 v223, v64, v65
	v_add_u32_e32 v68, 0x38000, v72
	global_store_dwordx4 v68, v[220:223], s[100:101] nt

; #define LAS __attribute__((address_space(3)))
; #define TR_LOAD(p) __builtin_nontemporal_load(p)
;     __device__ __forceinline__ int count() const { return (e0 - b0) + (e1 - b1) + (e2 - b2); }
; __device__ __forceinline__ void tr_all(const float* const* in, unsigned char* ws, LAS float* scr, int gw, int ngw, int lane, const TrRanges rg) {
;     const int TR_CNT = rg.count();
;     if (gw >= TR_CNT) return;
;     TrItem cur = tr_decode(rg.item(gw), in, ws, lane);
;     f32x4 v[16];
; #pragma unroll
;     for (int i = 0; i < 16; ++i) v[i] = TR_LOAD((const f32x4*)(cur.src + (size_t)(4 * i) * cur.N));
;     for (int it = gw; it < TR_CNT; it += ngw) {
;         const int nit = it + ngw; const bool hn = nit < TR_CNT;
;         TrItem nx = cur; f32x4 w[16];
;         if (hn) { nx = tr_decode(rg.item(nit), in, ws, lane);
; __global__ void __launch_bounds__(512, 2) mk_fwd(Args a) {
;     ...
;         if (G == 256 && bid >= 160) { __syncthreads(); tr_all(a.in, ws, (LAS float*)(lds + wid * 16640), (bid - 160) * 8 + wid, 96 * 8, lane, TrRanges{11136, 13184, 16256, W2GU_SPLIT, 0, 0});
.LBB0_876:
	s_cmpk_lg_i32 s86, 0x100
	s_cselect_b64 s[0:1], -1, 0
	s_cmpk_lt_i32 s87, 0xa0
	s_cselect_b64 s[2:3], -1, 0
	s_or_b64 s[0:1], s[2:3], s[0:1]
	s_and_b64 vcc, exec, s[0:1]
	s_cbranch_vccnz .LBB0_956
	s_add_i32 s33, s87, 0xffffff60
	s_lshl_b32 s0, s33, 3
	v_readlane_b32 s1, v254, 34
	s_add_i32 s34, s1, s0
	s_cmpk_gt_i32 s34, 0x7ff
	s_waitcnt vmcnt(0)
	s_barrier
	s_cbranch_scc1 .LBB0_947
	s_cmpk_lt_i32 s34, 0x800
	s_movk_i32 s0, 0x2b80
	s_cselect_b32 s14, s0, 0x3780
	s_add_i32 s14, s14, s34
	s_cmpk_lt_u32 s14, 0x2f80
	s_mov_b32 s22, 8
	s_cbranch_scc1 .LBB0_882
	s_cmpk_lt_u32 s14, 0x3380
	s_cbranch_scc1 .LBB0_883
	s_cmpk_lt_u32 s14, 0x3b80
	s_cbranch_scc1 .LBB0_884
	s_cmpk_lt_u32 s14, 0x3f80
	s_cselect_b64 s[8:9], -1, 0
	s_cmpk_gt_u32 s14, 0x3f7f
	s_cselect_b64 s[20:21], -1, 0
	s_and_b64 s[0:1], s[8:9], exec
	v_readlane_b32 s24, v254, 4
	v_readlane_b32 s40, v254, 18
	s_movk_i32 s2, 0xc480
	s_mov_b32 s0, 0x8700000
	v_readlane_b32 s25, v254, 5
	v_readlane_b32 s26, v254, 6
	v_readlane_b32 s27, v254, 7
	v_readlane_b32 s28, v254, 8
	v_readlane_b32 s29, v254, 9
	v_readlane_b32 s54, v254, 32
	v_readlane_b32 s55, v254, 33
	s_movk_i32 s4, 0x800
	s_cselect_b32 s15, s2, 0xffffc080
	s_cselect_b32 s0, s0, 0x8f00000
	s_mov_b32 s1, 0
	s_cselect_b32 s3, 0, s25
	s_cselect_b32 s2, 0, s24
	s_cselect_b32 s19, 0, s29
	s_cselect_b32 s18, 0, s28
	s_cselect_b32 s7, s55, s27
	s_cselect_b32 s6, s54, s26
	s_cselect_b32 s4, s4, 0x1600
	s_cselect_b32 s22, 8, 44
	v_readlane_b32 s30, v254, 10
	v_readlane_b32 s31, v254, 11
	v_readlane_b32 s41, v254, 19
	v_readlane_b32 s42, v254, 20
	v_readlane_b32 s43, v254, 21
	v_readlane_b32 s44, v254, 22
	v_readlane_b32 s45, v254, 23
	v_readlane_b32 s46, v254, 24
	v_readlane_b32 s47, v254, 25
	v_readlane_b32 s48, v254, 26
	v_readlane_b32 s49, v254, 27
	v_readlane_b32 s50, v254, 28
	v_readlane_b32 s51, v254, 29
	v_readlane_b32 s52, v254, 30
	v_readlane_b32 s53, v254, 31
	s_branch .LBB0_886

; __device__ __forceinline__ TrItem tr_decode(int it, const float* const* in, unsigned char* ws, int lane) {
;     int r = it, kind = 0, ndb = 32, N = D, K = D; const float *W, *W2 = nullptr, *gain = nullptr; bf16_t* WT; bool nts = false, woh = false;
;     if (r < 5632) { kind = 1; W = in[3]; W2 = in[4]; N = FF; ndb = 176; gain = in[2]; WT = (bf16_t*)(ws + WS_W1GU); }
;     else if ((r -= 5632) < 2816) { W = in[5]; K = FF; WT = (bf16_t*)(ws + WS_W1D); }
;     else if ((r -= 2816) < 2688) { kind = 2; W = in[7]; N = INC; ndb = 84; gain = in[6]; WT = (bf16_t*)(ws + WS_WIN); nts = true; }
;     else if ((r -= 2688) < 1024) { W = in[10]; WT = (bf16_t*)(ws + WS_WOUT); nts = true; }
;     else if ((r -= 1024) < 1024) { W = in[13]; gain = in[11]; WT = (bf16_t*)(ws + WS_WQ); nts = true; }
;     else if ((r -= 1024) < 2048) { W = in[14]; N = 2 * D; ndb = 64; gain = in[12]; WT = (bf16_t*)(ws + WS_WKV); }
;     else if ((r -= 2048) < 1024) { W = in[15]; WT = (bf16_t*)(ws + WS_WO); nts = true; woh = true; }
;     else if ((r -= 1024) < 5632) { kind = 1; W = in[17]; W2 = in[18]; N = FF; ndb = 176; gain = in[16]; WT = (bf16_t*)(ws + WS_W2GU); nts = true; }
;     else { r -= 5632; W = in[19]; K = FF; WT = (bf16_t*)(ws + WS_W2D); }
; __device__ __forceinline__ void tr_all(const float* const* in, unsigned char* ws, LAS float* scr, int gw, int ngw, int lane, const TrRanges rg) {
;     ...
;     for (int it = gw; it < TR_CNT; it += ngw) {
;         const int nit = it + ngw; const bool hn = nit < TR_CNT;
;         TrItem nx = cur; f32x4 w[16];
;         if (hn) { nx = tr_decode(rg.item(nit), in, ws, lane);
.LBB0_893:
	s_add_i32 s35, s6, 0x300
	s_cmpk_lt_i32 s35, 0x500
	s_cselect_b64 s[4:5], -1, 0
	s_cmpk_gt_i32 s35, 0x4ff
	s_cselect_b64 s[2:3], -1, 0
	s_and_b64 vcc, exec, s[2:3]
	v_mov_b64_e32 v[152:153], v[148:149]
	v_mov_b64_e32 v[154:155], v[146:147]
	s_mov_b32 s30, s0
	s_cbranch_vccnz .LBB0_942
	s_cmpk_lt_i32 s35, 0x500
	s_movk_i32 s7, 0x2e80
	s_cselect_b32 s20, s7, 0x3a80
	s_add_i32 s38, s20, s34
	s_add_i32 s20, s20, s6
	s_add_i32 s6, s20, 0x300
	s_cmpk_lt_i32 s6, 0x1600
	s_mov_b64 s[22:23], -1
	s_cbranch_scc1 .LBB0_904
	s_cmpk_gt_u32 s6, 0x20ff
	s_cbranch_scc0 .LBB0_905
	s_cmpk_gt_u32 s6, 0x2b7f
	s_cbranch_scc0 .LBB0_906
	s_cmpk_gt_u32 s6, 0x2f7f
	s_cbranch_scc0 .LBB0_907
	s_cmpk_gt_u32 s6, 0x337f
	s_cbranch_scc0 .LBB0_908
	s_cmpk_gt_u32 s6, 0x3b7f
	s_cbranch_scc0 .LBB0_909
	v_readlane_b32 s44, v254, 18
	v_readlane_b32 s58, v254, 32
	v_readlane_b32 s59, v254, 33
	s_cmpk_gt_u32 s6, 0x3f7f
	s_mov_b64 s[26:27], -1
	s_mov_b64 s[6:7], s[58:59]
	s_mov_b64 s[8:9], -1
	v_readlane_b32 s45, v254, 19
	v_readlane_b32 s46, v254, 20
	v_readlane_b32 s47, v254, 21
	v_readlane_b32 s48, v254, 22
	v_readlane_b32 s49, v254, 23
	v_readlane_b32 s50, v254, 24
	v_readlane_b32 s51, v254, 25
	v_readlane_b32 s52, v254, 26
	v_readlane_b32 s53, v254, 27
	v_readlane_b32 s54, v254, 28
	v_readlane_b32 s55, v254, 29
	v_readlane_b32 s56, v254, 30
	v_readlane_b32 s57, v254, 31
	s_cbranch_scc0 .LBB0_902
	v_readlane_b32 s44, v254, 4
	v_readlane_b32 s45, v254, 5
	v_readlane_b32 s46, v254, 6
	v_readlane_b32 s47, v254, 7
	v_readlane_b32 s48, v254, 8
	v_readlane_b32 s49, v254, 9
	s_add_i32 s40, s20, 0xffffc380
	s_mov_b64 s[8:9], 0
	v_readlane_b32 s50, v254, 10
	v_readlane_b32 s51, v254, 11
	s_mov_b64 s[6:7], s[46:47]
	s_mov_b64 s[18:19], s[48:49]
	s_mov_b64 s[14:15], s[44:45]

; #define LAS __attribute__((address_space(3)))
; #define TR_LOAD(p) __builtin_nontemporal_load(p)
; __device__ __forceinline__ TrItem tr_decode(int it, const float* const* in, unsigned char* ws, int lane) {
;     ...
;     const int rh = r >> 3, rl = r & 7, nq = ndb >> DL, kbh = rh / nq, dbh = rh - kbh * nq;
;     const int kb = (kbh << KL) + (rl >> DL), db = (dbh << DL) + (rl & ((1 << DL) - 1)), d0 = db * 64, k0 = kb * 64;
;     ...
;     const int kb = r / ndb, db = r - kb * ndb, d0 = db * 64, k0 = kb * 64;
;     ...
;     const int blk = d0 + 32 * ((lane & 15) >> 3);
;     const float* src = W; int s0 = blk;
;     if (kind == 1) { const int pn = blk >> 8, bj = (blk >> 7) & 1, o = blk & 127; src = bj ? W2 : W; s0 = pn * 128 + o; }
;     else if (kind == 2) s0 = win_src(blk);
;     TrItem t; t.src = src + (size_t)(k0 + (lane >> 4)) * N + s0 + 4 * (lane & 7); t.gain = gain ? gain + k0 + 8 * (lane & 7) : nullptr;
;     t.dst = WT + (size_t)(d0 + (lane >> 3)) * K + k0 + 8 * (lane & 7); t.N = N; t.K = K; t.nts = nts && TR_NTS;
; __device__ __forceinline__ void tr_all(const float* const* in, unsigned char* ws, LAS float* scr, int gw, int ngw, int lane, const TrRanges rg) {
;     ...
;     f32x4 v[16];
; #pragma unroll
;     for (int i = 0; i < 16; ++i) v[i] = TR_LOAD((const f32x4*)(cur.src + (size_t)(4 * i) * cur.N));
;     for (int it = gw; it < TR_CNT; it += ngw) {
;         const int nit = it + ngw; const bool hn = nit < TR_CNT;
;         TrItem nx = cur; f32x4 w[16];
;         if (hn) { nx = tr_decode(rg.item(nit), in, ws, lane);
; #pragma unroll
;             for (int i = 0; i < 16; ++i) w[i] = TR_LOAD((const f32x4*)(nx.src + (size_t)(4 * i) * nx.N)); }
;         LAS float* wp = scr + (lane >> 4) * 65 + 4 * (lane & 15);
; #pragma unroll
;         for (int i = 0; i < 16; ++i) { wp[(4 * i) * 65 + 0] = v[i][0]; wp[(4 * i) * 65 + 1] = v[i][1]; wp[(4 * i) * 65 + 2] = v[i][2]; wp[(4 * i) * 65 + 3] = v[i][3]; }
.Lseam_cv_3:
	s_cmp_lt_u32 s98, 2
	s_cbranch_scc1 .LBB0_1006
	s_cmp_gt_u32 s98, 5
	s_cbranch_scc1 .Lseam_cv_3_1
	s_mov_b64 exec, -1
	s_lshl_b32 s99, s87, 2
	s_add_i32 s99, s99, s98
	s_add_i32 s99, s99, 0x11fe
	s_lshr_b32 s100, s99, 3
	s_mul_i32 s101, s100, 0x5d2
	s_lshr_b32 s101, s101, 16
	s_mul_i32 vcc_lo, s101, 44
	s_sub_i32 s100, s100, vcc_lo
	s_and_b32 vcc_lo, s99, 7
	s_lshr_b32 vcc_hi, vcc_lo, 2
	s_lshl_b32 s101, s101, 1
	s_add_i32 s101, s101, vcc_hi
	s_and_b32 vcc_lo, vcc_lo, 3
	s_lshl_b32 s100, s100, 2
	s_add_i32 s100, s100, vcc_lo
	s_lshl_b32 s101, s101, 6
	s_lshl_b32 s100, s100, 6
	v_and_b32_e32 v66, 63, v1
	v_lshrrev_b32_e32 v67, 4, v66
	v_and_b32_e32 v68, 15, v66
	v_and_b32_e32 v73, 7, v66
	v_lshrrev_b32_e32 v72, 3, v66
	s_mul_i32 s99, s98, 0x4100
	v_mul_u32_u24_e32 v70, 0x104, v67
	v_lshl_add_u32 v70, v68, 4, v70
	v_add_u32_e32 v70, s99, v70
	v_mul_u32_u24_e32 v71, 0x820, v73
	v_lshl_add_u32 v71, v72, 2, v71
	v_add_u32_e32 v71, s99, v71
	s_mul_i32 s99, s101, 0x1600
	s_lshr_b32 vcc_lo, s100, 8
	s_lshl_b32 vcc_lo, vcc_lo, 7
	s_add_i32 s99, s99, vcc_lo
	s_and_b32 vcc_lo, s100, 0x7f
	s_add_i32 s99, s99, vcc_lo
	s_lshl_b32 s99, s99, 2
	v_mul_u32_u24_e32 v69, 0x5800, v67
	v_lshl_add_u32 v69, v68, 4, v69
	v_add_u32_e32 v69, s99, v69
	s_lshl_b32 s99, s100, 12
	s_lshl_b32 vcc_lo, s101, 1
	s_add_i32 s99, s99, vcc_lo
	v_lshlrev_b32_e32 v72, 12, v72
	v_lshl_add_u32 v72, v73, 4, v72
	v_add_u32_e32 v72, s99, v72
	s_lshl_b32 s99, s101, 2
	v_lshlrev_b32_e32 v73, 5, v73
	v_add_u32_e32 v73, s99, v73
	s_nop 0
	s_bitcmp1_b32 s100, 7
	v_readlane_b32 s100, v254, 6
	v_readlane_b32 s101, v254, 7
	v_readlane_b32 s98, v254, 8
	v_readlane_b32 s99, v254, 9
	s_nop 3
	s_cselect_b32 s100, s98, s100
	s_cselect_b32 s101, s99, s101
	v_readlane_b32 s98, v254, 4
	v_readlane_b32 s99, v254, 5
	global_load_dwordx4 v[2:5], v69, s[100:101] nt
	v_add_u32_e32 v68, 0x16000, v69
	global_load_dwordx4 v[6:9], v68, s[100:101] nt
	v_add_u32_e32 v67, 0x2c000, v69
	global_load_dwordx4 v[10:13], v67, s[100:101] nt
	v_add_u32_e32 v68, 0x42000, v69
	global_load_dwordx4 v[14:17], v68, s[100:101] nt
	v_add_u32_e32 v67, 0x58000, v69
	global_load_dwordx4 v[18:21], v67, s[100:101] nt
	v_add_u32_e32 v68, 0x6e000, v69
	global_load_dwordx4 v[22:25], v68, s[100:101] nt
	v_add_u32_e32 v67, 0x84000, v69
	global_load_dwordx4 v[26:29], v67, s[100:101] nt
	v_add_u32_e32 v68, 0x9a000, v69
	global_load_dwordx4 v[30:33], v68, s[100:101] nt
	v_add_u32_e32 v67, 0xb0000, v69
	global_load_dwordx4 v[34:37], v67, s[100:101] nt
	v_add_u32_e32 v68, 0xc6000, v69
	global_load_dwordx4 v[38:41], v68, s[100:101] nt
	v_add_u32_e32 v67, 0xdc000, v69
	global_load_dwordx4 v[42:45], v67, s[100:101] nt
	v_add_u32_e32 v68, 0xf2000, v69
	global_load_dwordx4 v[46:49], v68, s[100:101] nt
	v_add_u32_e32 v67, 0x108000, v69
	global_load_dwordx4 v[50:53], v67, s[100:101] nt
	v_add_u32_e32 v68, 0x11e000, v69
	global_load_dwordx4 v[54:57], v68, s[100:101] nt
	v_add_u32_e32 v67, 0x134000, v69
	global_load_dwordx4 v[58:61], v67, s[100:101] nt
	v_add_u32_e32 v68, 0x14a000, v69
	global_load_dwordx4 v[62:65], v68, s[100:101] nt
	global_load_dwordx4 v[74:77], v73, s[98:99]
	global_load_dwordx4 v[78:81], v73, s[98:99] offset:16
	s_waitcnt vmcnt(17)
	ds_write_b32 v70, v2
	ds_write_b32 v70, v3 offset:4
	ds_write_b32 v70, v4 offset:8
	ds_write_b32 v70, v5 offset:12
	s_waitcnt vmcnt(16)
	ds_write_b32 v70, v6 offset:1040
	ds_write_b32 v70, v7 offset:1044
	ds_write_b32 v70, v8 offset:1048
	ds_write_b32 v70, v9 offset:1052
	s_waitcnt vmcnt(15)
	ds_write_b32 v70, v10 offset:2080
	ds_write_b32 v70, v11 offset:2084
	ds_write_b32 v70, v12 offset:2088
	ds_write_b32 v70, v13 offset:2092
	s_waitcnt vmcnt(14)
	ds_write_b32 v70, v14 offset:3120
	ds_write_b32 v70, v15 offset:3124
	ds_write_b32 v70, v16 offset:3128
	ds_write_b32 v70, v17 offset:3132
	s_waitcnt vmcnt(13)
	ds_write_b32 v70, v18 offset:4160
	ds_write_b32 v70, v19 offset:4164
	ds_write_b32 v70, v20 offset:4168
	ds_write_b32 v70, v21 offset:4172
	s_waitcnt vmcnt(12)
	ds_write_b32 v70, v22 offset:5200
	ds_write_b32 v70, v23 offset:5204
	ds_write_b32 v70, v24 offset:5208
	ds_write_b32 v70, v25 offset:5212
	s_waitcnt vmcnt(11)
	ds_write_b32 v70, v26 offset:6240
	ds_write_b32 v70, v27 offset:6244
	ds_write_b32 v70, v28 offset:6248
	ds_write_b32 v70, v29 offset:6252
	s_waitcnt vmcnt(10)
	ds_write_b32 v70, v30 offset:7280
	ds_write_b32 v70, v31 offset:7284
	ds_write_b32 v70, v32 offset:7288
	ds_write_b32 v70, v33 offset:7292
	s_waitcnt vmcnt(9)
	ds_write_b32 v70, v34 offset:8320
	ds_write_b32 v70, v35 offset:8324
	ds_write_b32 v70, v36 offset:8328
	ds_write_b32 v70, v37 offset:8332
	s_waitcnt vmcnt(8)
	ds_write_b32 v70, v38 offset:9360
	ds_write_b32 v70, v39 offset:9364
	ds_write_b32 v70, v40 offset:9368
	ds_write_b32 v70, v41 offset:9372
	s_waitcnt vmcnt(7)
	ds_write_b32 v70, v42 offset:10400
	ds_write_b32 v70, v43 offset:10404
	ds_write_b32 v70, v44 offset:10408
	ds_write_b32 v70, v45 offset:10412
	s_waitcnt vmcnt(6)
	ds_write_b32 v70, v46 offset:11440
	ds_write_b32 v70, v47 offset:11444
	ds_write_b32 v70, v48 offset:11448
	ds_write_b32 v70, v49 offset:11452
	s_waitcnt vmcnt(5)
	ds_write_b32 v70, v50 offset:12480
	ds_write_b32 v70, v51 offset:12484
	ds_write_b32 v70, v52 offset:12488
	ds_write_b32 v70, v53 offset:12492
	s_waitcnt vmcnt(4)
	ds_write_b32 v70, v54 offset:13520
	ds_write_b32 v70, v55 offset:13524
	ds_write_b32 v70, v56 offset:13528
	ds_write_b32 v70, v57 offset:13532
	s_waitcnt vmcnt(3)
	ds_write_b32 v70, v58 offset:14560
	ds_write_b32 v70, v59 offset:14564
	ds_write_b32 v70, v60 offset:14568
	ds_write_b32 v70, v61 offset:14572
	s_waitcnt vmcnt(2)
; #define LAS __attribute__((address_space(3)))
; __device__ __forceinline__ unsigned cvtpk(float lo, float hi) { f32x2_t v = {lo, hi}; bf16x2_t b = __builtin_convertvector(v, bf16x2_t); return __builtin_bit_cast(unsigned, b); }
; __device__ __forceinline__ void tr_all(const float* const* in, unsigned char* ws, LAS float* scr, int gw, int ngw, int lane, const TrRanges rg) {
;     ...
;         for (int i = 0; i < 16; ++i) { wp[(4 * i) * 65 + 0] = v[i][0]; wp[(4 * i) * 65 + 1] = v[i][1]; wp[(4 * i) * 65 + 2] = v[i][2]; wp[(4 * i) * 65 + 3] = v[i][3]; }
;         f32x4 g0 = {1.f, 1.f, 1.f, 1.f}, g1 = {1.f, 1.f, 1.f, 1.f};
;         if (cur.gain) { g0 = *(const f32x4*)cur.gain; g1 = *(const f32x4*)(cur.gain + 4); }
;         asm volatile("s_waitcnt lgkmcnt(0)" ::: "memory");
;         const LAS float* rp = scr + (8 * (lane & 7)) * 65 + (lane >> 3);
; #pragma unroll
;         for (int j = 0; j < 8; ++j) { const LAS float* s = rp + 8 * j;
;             u32x4 o; o.x = cvtpk(s[0 * 65] * g0[0], s[1 * 65] * g0[1]); o.y = cvtpk(s[2 * 65] * g0[2], s[3 * 65] * g0[3]);
;             o.z = cvtpk(s[4 * 65] * g1[0], s[5 * 65] * g1[1]); o.w = cvtpk(s[6 * 65] * g1[2], s[7 * 65] * g1[3]);
;             if (cur.nts) __builtin_nontemporal_store(o, (u32x4*)(cur.dst + (size_t)(8 * j) * cur.K)); else *(u32x4*)(cur.dst + (size_t)(8 * j) * cur.K) = o; }
	ds_write_b32 v70, v62 offset:15600
	ds_write_b32 v70, v63 offset:15604
	ds_write_b32 v70, v64 offset:15608
	ds_write_b32 v70, v65 offset:15612
	s_add_u32 s100, s84, 0x8f00000
	s_addc_u32 s101, s85, 0
	s_waitcnt vmcnt(0) lgkmcnt(0)
	ds_read_b32 v2, v71
	ds_read_b32 v3, v71 offset:260
	ds_read_b32 v4, v71 offset:520
	ds_read_b32 v5, v71 offset:780
	ds_read_b32 v6, v71 offset:1040
	ds_read_b32 v7, v71 offset:1300
	ds_read_b32 v8, v71 offset:1560
	ds_read_b32 v9, v71 offset:1820
	ds_read_b32 v10, v71 offset:32
	ds_read_b32 v11, v71 offset:292
	ds_read_b32 v12, v71 offset:552
	ds_read_b32 v13, v71 offset:812
	ds_read_b32 v14, v71 offset:1072
	ds_read_b32 v15, v71 offset:1332
	ds_read_b32 v16, v71 offset:1592
	ds_read_b32 v17, v71 offset:1852
	ds_read_b32 v18, v71 offset:64
	ds_read_b32 v19, v71 offset:324
	ds_read_b32 v20, v71 offset:584
	ds_read_b32 v21, v71 offset:844
	ds_read_b32 v22, v71 offset:1104
	ds_read_b32 v23, v71 offset:1364
	ds_read_b32 v24, v71 offset:1624
	ds_read_b32 v25, v71 offset:1884
	ds_read_b32 v26, v71 offset:96
	ds_read_b32 v27, v71 offset:356
	ds_read_b32 v28, v71 offset:616
	ds_read_b32 v29, v71 offset:876
	ds_read_b32 v30, v71 offset:1136
	ds_read_b32 v31, v71 offset:1396
	ds_read_b32 v32, v71 offset:1656
	ds_read_b32 v33, v71 offset:1916
	ds_read_b32 v34, v71 offset:128
	ds_read_b32 v35, v71 offset:388
	ds_read_b32 v36, v71 offset:648
	ds_read_b32 v37, v71 offset:908
	ds_read_b32 v38, v71 offset:1168
	ds_read_b32 v39, v71 offset:1428
	ds_read_b32 v40, v71 offset:1688
	ds_read_b32 v41, v71 offset:1948
	ds_read_b32 v42, v71 offset:160
	ds_read_b32 v43, v71 offset:420
	ds_read_b32 v44, v71 offset:680
	ds_read_b32 v45, v71 offset:940
	ds_read_b32 v46, v71 offset:1200
	ds_read_b32 v47, v71 offset:1460
	ds_read_b32 v48, v71 offset:1720
	ds_read_b32 v49, v71 offset:1980
	ds_read_b32 v50, v71 offset:192
	ds_read_b32 v51, v71 offset:452
	ds_read_b32 v52, v71 offset:712
	ds_read_b32 v53, v71 offset:972
	ds_read_b32 v54, v71 offset:1232
	ds_read_b32 v55, v71 offset:1492
	ds_read_b32 v56, v71 offset:1752
	ds_read_b32 v57, v71 offset:2012
	ds_read_b32 v58, v71 offset:224
	ds_read_b32 v59, v71 offset:484
	ds_read_b32 v60, v71 offset:744
	ds_read_b32 v61, v71 offset:1004
	ds_read_b32 v62, v71 offset:1264
	ds_read_b32 v63, v71 offset:1524
	ds_read_b32 v64, v71 offset:1784
	ds_read_b32 v65, v71 offset:2044
	s_waitcnt lgkmcnt(15)
	v_mul_f32_e32 v2, v2, v74
	v_mul_f32_e32 v3, v3, v75
	v_mul_f32_e32 v4, v4, v76
	v_mul_f32_e32 v5, v5, v77
	v_mul_f32_e32 v6, v6, v78
	v_mul_f32_e32 v7, v7, v79
	v_mul_f32_e32 v8, v8, v80
	v_mul_f32_e32 v9, v9, v81
	v_cvt_pk_bf16_f32 v192, v2, v3
	v_cvt_pk_bf16_f32 v193, v4, v5
	v_cvt_pk_bf16_f32 v194, v6, v7
	v_cvt_pk_bf16_f32 v195, v8, v9
	global_store_dwordx4 v72, v[192:195], s[100:101] nt
	s_waitcnt lgkmcnt(15)
	v_mul_f32_e32 v10, v10, v74
	v_mul_f32_e32 v11, v11, v75
	v_mul_f32_e32 v12, v12, v76
	v_mul_f32_e32 v13, v13, v77
	v_mul_f32_e32 v14, v14, v78
	v_mul_f32_e32 v15, v15, v79
	v_mul_f32_e32 v16, v16, v80
	v_mul_f32_e32 v17, v17, v81
	v_cvt_pk_bf16_f32 v196, v10, v11
	v_cvt_pk_bf16_f32 v197, v12, v13
	v_cvt_pk_bf16_f32 v198, v14, v15
	v_cvt_pk_bf16_f32 v199, v16, v17
	v_add_u32_e32 v68, 0x8000, v72
	global_store_dwordx4 v68, v[196:199], s[100:101] nt
	s_waitcnt lgkmcnt(15)
	v_mul_f32_e32 v18, v18, v74
	v_mul_f32_e32 v19, v19, v75
	v_mul_f32_e32 v20, v20, v76
	v_mul_f32_e32 v21, v21, v77
	v_mul_f32_e32 v22, v22, v78
	v_mul_f32_e32 v23, v23, v79
	v_mul_f32_e32 v24, v24, v80
	v_mul_f32_e32 v25, v25, v81
	v_cvt_pk_bf16_f32 v200, v18, v19
	v_cvt_pk_bf16_f32 v201, v20, v21
	v_cvt_pk_bf16_f32 v202, v22, v23
	v_cvt_pk_bf16_f32 v203, v24, v25
	v_add_u32_e32 v67, 0x10000, v72
	global_store_dwordx4 v67, v[200:203], s[100:101] nt
	s_waitcnt lgkmcnt(15)
	v_mul_f32_e32 v26, v26, v74
	v_mul_f32_e32 v27, v27, v75
	v_mul_f32_e32 v28, v28, v76
	v_mul_f32_e32 v29, v29, v77
	v_mul_f32_e32 v30, v30, v78
	v_mul_f32_e32 v31, v31, v79
	v_mul_f32_e32 v32, v32, v80
	v_mul_f32_e32 v33, v33, v81
	v_cvt_pk_bf16_f32 v204, v26, v27
	v_cvt_pk_bf16_f32 v205, v28, v29
	v_cvt_pk_bf16_f32 v206, v30, v31
	v_cvt_pk_bf16_f32 v207, v32, v33
	v_add_u32_e32 v68, 0x18000, v72
	global_store_dwordx4 v68, v[204:207], s[100:101] nt
	s_waitcnt lgkmcnt(15)
	v_mul_f32_e32 v34, v34, v74
	v_mul_f32_e32 v35, v35, v75
	v_mul_f32_e32 v36, v36, v76
	v_mul_f32_e32 v37, v37, v77
	v_mul_f32_e32 v38, v38, v78
	v_mul_f32_e32 v39, v39, v79
	v_mul_f32_e32 v40, v40, v80
	v_mul_f32_e32 v41, v41, v81
	v_cvt_pk_bf16_f32 v208, v34, v35
	v_cvt_pk_bf16_f32 v209, v36, v37
	v_cvt_pk_bf16_f32 v210, v38, v39
	v_cvt_pk_bf16_f32 v211, v40, v41
	v_add_u32_e32 v67, 0x20000, v72
	global_store_dwordx4 v67, v[208:211], s[100:101] nt
	s_waitcnt lgkmcnt(15)
	v_mul_f32_e32 v42, v42, v74
	v_mul_f32_e32 v43, v43, v75
	v_mul_f32_e32 v44, v44, v76
	v_mul_f32_e32 v45, v45, v77
	v_mul_f32_e32 v46, v46, v78
	v_mul_f32_e32 v47, v47, v79
	v_mul_f32_e32 v48, v48, v80
	v_mul_f32_e32 v49, v49, v81
	v_cvt_pk_bf16_f32 v212, v42, v43
	v_cvt_pk_bf16_f32 v213, v44, v45
	v_cvt_pk_bf16_f32 v214, v46, v47
	v_cvt_pk_bf16_f32 v215, v48, v49
	v_add_u32_e32 v68, 0x28000, v72
	global_store_dwordx4 v68, v[212:215], s[100:101] nt
	s_waitcnt lgkmcnt(8)
	v_mul_f32_e32 v50, v50, v74
	v_mul_f32_e32 v51, v51, v75
	v_mul_f32_e32 v52, v52, v76
	v_mul_f32_e32 v53, v53, v77
	v_mul_f32_e32 v54, v54, v78
	v_mul_f32_e32 v55, v55, v79
	v_mul_f32_e32 v56, v56, v80
	v_mul_f32_e32 v57, v57, v81
	v_cvt_pk_bf16_f32 v216, v50, v51
	v_cvt_pk_bf16_f32 v217, v52, v53
	v_cvt_pk_bf16_f32 v218, v54, v55
	v_cvt_pk_bf16_f32 v219, v56, v57
	v_add_u32_e32 v67, 0x30000, v72
	global_store_dwordx4 v67, v[216:219], s[100:101] nt
	s_waitcnt lgkmcnt(0)
	v_mul_f32_e32 v58, v58, v74
	v_mul_f32_e32 v59, v59, v75
	v_mul_f32_e32 v60, v60, v76
	v_mul_f32_e32 v61, v61, v77
	v_mul_f32_e32 v62, v62, v78
	v_mul_f32_e32 v63, v63, v79
	v_mul_f32_e32 v64, v64, v80
	v_mul_f32_e32 v65, v65, v81
	v_cvt_pk_bf16_f32 v220, v58, v59
	v_cvt_pk_bf16_f32 v221, v60, v61
	v_cvt_pk_bf16_f32 v222, v62, v63
	v_cvt_pk_bf16_f32 v223, v64, v65
	v_add_u32_e32 v68, 0x38000, v72
	global_store_dwordx4 v68, v[220:223], s[100:101] nt
	s_branch .LBB0_1006
; #define LAS __attribute__((address_space(3)))
; #define TR_LOAD(p) __builtin_nontemporal_load(p)
; __device__ __forceinline__ TrItem tr_decode(int it, const float* const* in, unsigned char* ws, int lane) {
;     ...
;     const int rh = r >> 3, rl = r & 7, nq = ndb >> DL, kbh = rh / nq, dbh = rh - kbh * nq;
;     const int kb = (kbh << KL) + (rl >> DL), db = (dbh << DL) + (rl & ((1 << DL) - 1)), d0 = db * 64, k0 = kb * 64;
;     ...
;     const int kb = r / ndb, db = r - kb * ndb, d0 = db * 64, k0 = kb * 64;
;     ...
;     const int blk = d0 + 32 * ((lane & 15) >> 3);
;     const float* src = W; int s0 = blk;
;     if (kind == 1) { const int pn = blk >> 8, bj = (blk >> 7) & 1, o = blk & 127; src = bj ? W2 : W; s0 = pn * 128 + o; }
;     else if (kind == 2) s0 = win_src(blk);
;     TrItem t; t.src = src + (size_t)(k0 + (lane >> 4)) * N + s0 + 4 * (lane & 7); t.gain = gain ? gain + k0 + 8 * (lane & 7) : nullptr;
;     t.dst = WT + (size_t)(d0 + (lane >> 3)) * K + k0 + 8 * (lane & 7); t.N = N; t.K = K; t.nts = nts && TR_NTS;
; __device__ __forceinline__ void tr_all(const float* const* in, unsigned char* ws, LAS float* scr, int gw, int ngw, int lane, const TrRanges rg) {
;     ...
;     f32x4 v[16];
; #pragma unroll
;     for (int i = 0; i < 16; ++i) v[i] = TR_LOAD((const f32x4*)(cur.src + (size_t)(4 * i) * cur.N));
;     for (int it = gw; it < TR_CNT; it += ngw) {
;         const int nit = it + ngw; const bool hn = nit < TR_CNT;
;         TrItem nx = cur; f32x4 w[16];
;         if (hn) { nx = tr_decode(rg.item(nit), in, ws, lane);
; #pragma unroll
;             for (int i = 0; i < 16; ++i) w[i] = TR_LOAD((const f32x4*)(nx.src + (size_t)(4 * i) * nx.N)); }
;         LAS float* wp = scr + (lane >> 4) * 65 + 4 * (lane & 15);
; #pragma unroll
;         for (int i = 0; i < 16; ++i) { wp[(4 * i) * 65 + 0] = v[i][0]; wp[(4 * i) * 65 + 1] = v[i][1]; wp[(4 * i) * 65 + 2] = v[i][2]; wp[(4 * i) * 65 + 3] = v[i][3]; }
.Lseam_cv_3_1:
	s_cmp_gt_u32 s98, 7
	s_cbranch_scc1 .LBB0_1006
	s_mov_b64 exec, -1
	s_lshl_b32 s99, s87, 1
	s_add_i32 s99, s99, s98
	s_add_i32 s99, s99, 0x1fa
	s_lshr_b32 s100, s99, 3
	s_mul_i32 s101, s100, 0x5d2
	s_lshr_b32 s101, s101, 16
	s_mul_i32 vcc_lo, s101, 44
	s_sub_i32 s100, s100, vcc_lo
	s_and_b32 vcc_lo, s99, 7
	s_lshr_b32 vcc_hi, vcc_lo, 2
	s_lshl_b32 s101, s101, 1
	s_add_i32 s101, s101, vcc_hi
	s_and_b32 vcc_lo, vcc_lo, 3
	s_lshl_b32 s100, s100, 2
	s_add_i32 s100, s100, vcc_lo
	s_lshl_b32 s101, s101, 6
	s_lshl_b32 s100, s100, 6
	v_and_b32_e32 v66, 63, v1
	v_lshrrev_b32_e32 v67, 4, v66
	v_and_b32_e32 v68, 15, v66
	v_and_b32_e32 v73, 7, v66
	v_lshrrev_b32_e32 v72, 3, v66
	s_mul_i32 s99, s98, 0x4100
	v_mul_u32_u24_e32 v70, 0x104, v67
	v_lshl_add_u32 v70, v68, 4, v70
	v_add_u32_e32 v70, s99, v70
	v_mul_u32_u24_e32 v71, 0x820, v73
	v_lshl_add_u32 v71, v72, 2, v71
	v_add_u32_e32 v71, s99, v71
	s_mul_i32 s99, s101, 0x1600
	s_lshr_b32 vcc_lo, s100, 8
	s_lshl_b32 vcc_lo, vcc_lo, 7
	s_add_i32 s99, s99, vcc_lo
	s_and_b32 vcc_lo, s100, 0x7f
	s_add_i32 s99, s99, vcc_lo
	s_lshl_b32 s99, s99, 2
	v_mul_u32_u24_e32 v69, 0x5800, v67
	v_lshl_add_u32 v69, v68, 4, v69
	v_add_u32_e32 v69, s99, v69
	s_lshl_b32 s99, s100, 12
	s_lshl_b32 vcc_lo, s101, 1
	s_add_i32 s99, s99, vcc_lo
	v_lshlrev_b32_e32 v72, 12, v72
	v_lshl_add_u32 v72, v73, 4, v72
	v_add_u32_e32 v72, s99, v72
	s_lshl_b32 s99, s101, 2
	v_lshlrev_b32_e32 v73, 5, v73
	v_add_u32_e32 v73, s99, v73
	s_nop 0
	s_bitcmp1_b32 s100, 7
	v_readlane_b32 s100, v254, 6
	v_readlane_b32 s101, v254, 7
	v_readlane_b32 s98, v254, 8
	v_readlane_b32 s99, v254, 9
	s_nop 3
	s_cselect_b32 s100, s98, s100
	s_cselect_b32 s101, s99, s101
	v_readlane_b32 s98, v254, 4
	v_readlane_b32 s99, v254, 5
	global_load_dwordx4 v[2:5], v69, s[100:101] nt
	v_add_u32_e32 v68, 0x16000, v69
	global_load_dwordx4 v[6:9], v68, s[100:101] nt
	v_add_u32_e32 v67, 0x2c000, v69
	global_load_dwordx4 v[10:13], v67, s[100:101] nt
	v_add_u32_e32 v68, 0x42000, v69
	global_load_dwordx4 v[14:17], v68, s[100:101] nt
	v_add_u32_e32 v67, 0x58000, v69
	global_load_dwordx4 v[18:21], v67, s[100:101] nt
	v_add_u32_e32 v68, 0x6e000, v69
	global_load_dwordx4 v[22:25], v68, s[100:101] nt
	v_add_u32_e32 v67, 0x84000, v69
	global_load_dwordx4 v[26:29], v67, s[100:101] nt
	v_add_u32_e32 v68, 0x9a000, v69
	global_load_dwordx4 v[30:33], v68, s[100:101] nt
	v_add_u32_e32 v67, 0xb0000, v69
	global_load_dwordx4 v[34:37], v67, s[100:101] nt
	v_add_u32_e32 v68, 0xc6000, v69
	global_load_dwordx4 v[38:41], v68, s[100:101] nt
	v_add_u32_e32 v67, 0xdc000, v69
	global_load_dwordx4 v[42:45], v67, s[100:101] nt
	v_add_u32_e32 v68, 0xf2000, v69
	global_load_dwordx4 v[46:49], v68, s[100:101] nt
	v_add_u32_e32 v67, 0x108000, v69
	global_load_dwordx4 v[50:53], v67, s[100:101] nt
	v_add_u32_e32 v68, 0x11e000, v69
	global_load_dwordx4 v[54:57], v68, s[100:101] nt
	v_add_u32_e32 v67, 0x134000, v69
	global_load_dwordx4 v[58:61], v67, s[100:101] nt
	v_add_u32_e32 v68, 0x14a000, v69
	global_load_dwordx4 v[62:65], v68, s[100:101] nt
	global_load_dwordx4 v[74:77], v73, s[98:99]
	global_load_dwordx4 v[78:81], v73, s[98:99] offset:16
	s_waitcnt vmcnt(17)
	ds_write_b32 v70, v2
	ds_write_b32 v70, v3 offset:4
	ds_write_b32 v70, v4 offset:8
	ds_write_b32 v70, v5 offset:12
	s_waitcnt vmcnt(16)
	ds_write_b32 v70, v6 offset:1040
	ds_write_b32 v70, v7 offset:1044
	ds_write_b32 v70, v8 offset:1048
	ds_write_b32 v70, v9 offset:1052
	s_waitcnt vmcnt(15)
	ds_write_b32 v70, v10 offset:2080
	ds_write_b32 v70, v11 offset:2084
	ds_write_b32 v70, v12 offset:2088
	ds_write_b32 v70, v13 offset:2092
	s_waitcnt vmcnt(14)
	ds_write_b32 v70, v14 offset:3120
	ds_write_b32 v70, v15 offset:3124
	ds_write_b32 v70, v16 offset:3128
	ds_write_b32 v70, v17 offset:3132
	s_waitcnt vmcnt(13)
	ds_write_b32 v70, v18 offset:4160
	ds_write_b32 v70, v19 offset:4164
	ds_write_b32 v70, v20 offset:4168
	ds_write_b32 v70, v21 offset:4172
	s_waitcnt vmcnt(12)
	ds_write_b32 v70, v22 offset:5200
	ds_write_b32 v70, v23 offset:5204
	ds_write_b32 v70, v24 offset:5208
	ds_write_b32 v70, v25 offset:5212
	s_waitcnt vmcnt(11)
	ds_write_b32 v70, v26 offset:6240
	ds_write_b32 v70, v27 offset:6244
	ds_write_b32 v70, v28 offset:6248
	ds_write_b32 v70, v29 offset:6252
	s_waitcnt vmcnt(10)
	ds_write_b32 v70, v30 offset:7280
	ds_write_b32 v70, v31 offset:7284
	ds_write_b32 v70, v32 offset:7288
	ds_write_b32 v70, v33 offset:7292
	s_waitcnt vmcnt(9)
	ds_write_b32 v70, v34 offset:8320
	ds_write_b32 v70, v35 offset:8324
	ds_write_b32 v70, v36 offset:8328
	ds_write_b32 v70, v37 offset:8332
	s_waitcnt vmcnt(8)
	ds_write_b32 v70, v38 offset:9360
	ds_write_b32 v70, v39 offset:9364
	ds_write_b32 v70, v40 offset:9368
	ds_write_b32 v70, v41 offset:9372
	s_waitcnt vmcnt(7)
	ds_write_b32 v70, v42 offset:10400
	ds_write_b32 v70, v43 offset:10404
	ds_write_b32 v70, v44 offset:10408
	ds_write_b32 v70, v45 offset:10412
	s_waitcnt vmcnt(6)
	ds_write_b32 v70, v46 offset:11440
	ds_write_b32 v70, v47 offset:11444
	ds_write_b32 v70, v48 offset:11448
	ds_write_b32 v70, v49 offset:11452
	s_waitcnt vmcnt(5)
	ds_write_b32 v70, v50 offset:12480
	ds_write_b32 v70, v51 offset:12484
	ds_write_b32 v70, v52 offset:12488
	ds_write_b32 v70, v53 offset:12492
	s_waitcnt vmcnt(4)
	ds_write_b32 v70, v54 offset:13520
	ds_write_b32 v70, v55 offset:13524
	ds_write_b32 v70, v56 offset:13528
	ds_write_b32 v70, v57 offset:13532
	s_waitcnt vmcnt(3)
	ds_write_b32 v70, v58 offset:14560
	ds_write_b32 v70, v59 offset:14564
	ds_write_b32 v70, v60 offset:14568
	ds_write_b32 v70, v61 offset:14572
	s_waitcnt vmcnt(2)
; #define LAS __attribute__((address_space(3)))
; __device__ __forceinline__ unsigned cvtpk(float lo, float hi) { f32x2_t v = {lo, hi}; bf16x2_t b = __builtin_convertvector(v, bf16x2_t); return __builtin_bit_cast(unsigned, b); }
; __device__ __forceinline__ void tr_all(const float* const* in, unsigned char* ws, LAS float* scr, int gw, int ngw, int lane, const TrRanges rg) {
;     ...
;         for (int i = 0; i < 16; ++i) { wp[(4 * i) * 65 + 0] = v[i][0]; wp[(4 * i) * 65 + 1] = v[i][1]; wp[(4 * i) * 65 + 2] = v[i][2]; wp[(4 * i) * 65 + 3] = v[i][3]; }
;         f32x4 g0 = {1.f, 1.f, 1.f, 1.f}, g1 = {1.f, 1.f, 1.f, 1.f};
;         if (cur.gain) { g0 = *(const f32x4*)cur.gain; g1 = *(const f32x4*)(cur.gain + 4); }
;         asm volatile("s_waitcnt lgkmcnt(0)" ::: "memory");
;         const LAS float* rp = scr + (8 * (lane & 7)) * 65 + (lane >> 3);
; #pragma unroll
;         for (int j = 0; j < 8; ++j) { const LAS float* s = rp + 8 * j;
;             u32x4 o; o.x = cvtpk(s[0 * 65] * g0[0], s[1 * 65] * g0[1]); o.y = cvtpk(s[2 * 65] * g0[2], s[3 * 65] * g0[3]);
;             o.z = cvtpk(s[4 * 65] * g1[0], s[5 * 65] * g1[1]); o.w = cvtpk(s[6 * 65] * g1[2], s[7 * 65] * g1[3]);
;             if (cur.nts) __builtin_nontemporal_store(o, (u32x4*)(cur.dst + (size_t)(8 * j) * cur.K)); else *(u32x4*)(cur.dst + (size_t)(8 * j) * cur.K) = o; }
	ds_write_b32 v70, v62 offset:15600
	ds_write_b32 v70, v63 offset:15604
	ds_write_b32 v70, v64 offset:15608
	ds_write_b32 v70, v65 offset:15612
	s_add_u32 s100, s84, 0x8f00000
	s_addc_u32 s101, s85, 0
	s_waitcnt vmcnt(0) lgkmcnt(0)
	ds_read_b32 v2, v71
	ds_read_b32 v3, v71 offset:260
	ds_read_b32 v4, v71 offset:520
	ds_read_b32 v5, v71 offset:780
	ds_read_b32 v6, v71 offset:1040
	ds_read_b32 v7, v71 offset:1300
	ds_read_b32 v8, v71 offset:1560
	ds_read_b32 v9, v71 offset:1820
	ds_read_b32 v10, v71 offset:32
	ds_read_b32 v11, v71 offset:292
	ds_read_b32 v12, v71 offset:552
	ds_read_b32 v13, v71 offset:812
	ds_read_b32 v14, v71 offset:1072
	ds_read_b32 v15, v71 offset:1332
	ds_read_b32 v16, v71 offset:1592
	ds_read_b32 v17, v71 offset:1852
	ds_read_b32 v18, v71 offset:64
	ds_read_b32 v19, v71 offset:324
	ds_read_b32 v20, v71 offset:584
	ds_read_b32 v21, v71 offset:844
	ds_read_b32 v22, v71 offset:1104
	ds_read_b32 v23, v71 offset:1364
	ds_read_b32 v24, v71 offset:1624
	ds_read_b32 v25, v71 offset:1884
	ds_read_b32 v26, v71 offset:96
	ds_read_b32 v27, v71 offset:356
	ds_read_b32 v28, v71 offset:616
	ds_read_b32 v29, v71 offset:876
	ds_read_b32 v30, v71 offset:1136
	ds_read_b32 v31, v71 offset:1396
	ds_read_b32 v32, v71 offset:1656
	ds_read_b32 v33, v71 offset:1916
	ds_read_b32 v34, v71 offset:128
	ds_read_b32 v35, v71 offset:388
	ds_read_b32 v36, v71 offset:648
	ds_read_b32 v37, v71 offset:908
	ds_read_b32 v38, v71 offset:1168
	ds_read_b32 v39, v71 offset:1428
	ds_read_b32 v40, v71 offset:1688
	ds_read_b32 v41, v71 offset:1948
	ds_read_b32 v42, v71 offset:160
	ds_read_b32 v43, v71 offset:420
	ds_read_b32 v44, v71 offset:680
	ds_read_b32 v45, v71 offset:940
	ds_read_b32 v46, v71 offset:1200
	ds_read_b32 v47, v71 offset:1460
	ds_read_b32 v48, v71 offset:1720
	ds_read_b32 v49, v71 offset:1980
	ds_read_b32 v50, v71 offset:192
	ds_read_b32 v51, v71 offset:452
	ds_read_b32 v52, v71 offset:712
	ds_read_b32 v53, v71 offset:972
	ds_read_b32 v54, v71 offset:1232
	ds_read_b32 v55, v71 offset:1492
	ds_read_b32 v56, v71 offset:1752
	ds_read_b32 v57, v71 offset:2012
	ds_read_b32 v58, v71 offset:224
	ds_read_b32 v59, v71 offset:484
	ds_read_b32 v60, v71 offset:744
	ds_read_b32 v61, v71 offset:1004
	ds_read_b32 v62, v71 offset:1264
	ds_read_b32 v63, v71 offset:1524
	ds_read_b32 v64, v71 offset:1784
	ds_read_b32 v65, v71 offset:2044
	s_waitcnt lgkmcnt(15)
	v_mul_f32_e32 v2, v2, v74
	v_mul_f32_e32 v3, v3, v75
	v_mul_f32_e32 v4, v4, v76
	v_mul_f32_e32 v5, v5, v77
	v_mul_f32_e32 v6, v6, v78
	v_mul_f32_e32 v7, v7, v79
	v_mul_f32_e32 v8, v8, v80
	v_mul_f32_e32 v9, v9, v81
	v_cvt_pk_bf16_f32 v192, v2, v3
	v_cvt_pk_bf16_f32 v193, v4, v5
	v_cvt_pk_bf16_f32 v194, v6, v7
	v_cvt_pk_bf16_f32 v195, v8, v9
	global_store_dwordx4 v72, v[192:195], s[100:101] nt
	s_waitcnt lgkmcnt(15)
	v_mul_f32_e32 v10, v10, v74
	v_mul_f32_e32 v11, v11, v75
	v_mul_f32_e32 v12, v12, v76
	v_mul_f32_e32 v13, v13, v77
	v_mul_f32_e32 v14, v14, v78
	v_mul_f32_e32 v15, v15, v79
	v_mul_f32_e32 v16, v16, v80
	v_mul_f32_e32 v17, v17, v81
	v_cvt_pk_bf16_f32 v196, v10, v11
	v_cvt_pk_bf16_f32 v197, v12, v13
	v_cvt_pk_bf16_f32 v198, v14, v15
	v_cvt_pk_bf16_f32 v199, v16, v17
	v_add_u32_e32 v68, 0x8000, v72
	global_store_dwordx4 v68, v[196:199], s[100:101] nt
	s_waitcnt lgkmcnt(15)
	v_mul_f32_e32 v18, v18, v74
	v_mul_f32_e32 v19, v19, v75
	v_mul_f32_e32 v20, v20, v76
	v_mul_f32_e32 v21, v21, v77
	v_mul_f32_e32 v22, v22, v78
	v_mul_f32_e32 v23, v23, v79
	v_mul_f32_e32 v24, v24, v80
	v_mul_f32_e32 v25, v25, v81
	v_cvt_pk_bf16_f32 v200, v18, v19
	v_cvt_pk_bf16_f32 v201, v20, v21
	v_cvt_pk_bf16_f32 v202, v22, v23
	v_cvt_pk_bf16_f32 v203, v24, v25
	v_add_u32_e32 v67, 0x10000, v72
	global_store_dwordx4 v67, v[200:203], s[100:101] nt
	s_waitcnt lgkmcnt(15)
	v_mul_f32_e32 v26, v26, v74
	v_mul_f32_e32 v27, v27, v75
	v_mul_f32_e32 v28, v28, v76
	v_mul_f32_e32 v29, v29, v77
	v_mul_f32_e32 v30, v30, v78
	v_mul_f32_e32 v31, v31, v79
	v_mul_f32_e32 v32, v32, v80
	v_mul_f32_e32 v33, v33, v81
	v_cvt_pk_bf16_f32 v204, v26, v27
	v_cvt_pk_bf16_f32 v205, v28, v29
	v_cvt_pk_bf16_f32 v206, v30, v31
	v_cvt_pk_bf16_f32 v207, v32, v33
	v_add_u32_e32 v68, 0x18000, v72
	global_store_dwordx4 v68, v[204:207], s[100:101] nt
	s_waitcnt lgkmcnt(15)
	v_mul_f32_e32 v34, v34, v74
	v_mul_f32_e32 v35, v35, v75
	v_mul_f32_e32 v36, v36, v76
	v_mul_f32_e32 v37, v37, v77
	v_mul_f32_e32 v38, v38, v78
	v_mul_f32_e32 v39, v39, v79
	v_mul_f32_e32 v40, v40, v80
	v_mul_f32_e32 v41, v41, v81
	v_cvt_pk_bf16_f32 v208, v34, v35
	v_cvt_pk_bf16_f32 v209, v36, v37
	v_cvt_pk_bf16_f32 v210, v38, v39
	v_cvt_pk_bf16_f32 v211, v40, v41
	v_add_u32_e32 v67, 0x20000, v72
	global_store_dwordx4 v67, v[208:211], s[100:101] nt
	s_waitcnt lgkmcnt(15)
	v_mul_f32_e32 v42, v42, v74
	v_mul_f32_e32 v43, v43, v75
	v_mul_f32_e32 v44, v44, v76
	v_mul_f32_e32 v45, v45, v77
	v_mul_f32_e32 v46, v46, v78
	v_mul_f32_e32 v47, v47, v79
	v_mul_f32_e32 v48, v48, v80
	v_mul_f32_e32 v49, v49, v81
	v_cvt_pk_bf16_f32 v212, v42, v43
	v_cvt_pk_bf16_f32 v213, v44, v45
	v_cvt_pk_bf16_f32 v214, v46, v47
	v_cvt_pk_bf16_f32 v215, v48, v49
	v_add_u32_e32 v68, 0x28000, v72
	global_store_dwordx4 v68, v[212:215], s[100:101] nt
	s_waitcnt lgkmcnt(8)
	v_mul_f32_e32 v50, v50, v74
	v_mul_f32_e32 v51, v51, v75
	v_mul_f32_e32 v52, v52, v76
	v_mul_f32_e32 v53, v53, v77
	v_mul_f32_e32 v54, v54, v78
	v_mul_f32_e32 v55, v55, v79
	v_mul_f32_e32 v56, v56, v80
	v_mul_f32_e32 v57, v57, v81
	v_cvt_pk_bf16_f32 v216, v50, v51
	v_cvt_pk_bf16_f32 v217, v52, v53
	v_cvt_pk_bf16_f32 v218, v54, v55
	v_cvt_pk_bf16_f32 v219, v56, v57
	v_add_u32_e32 v67, 0x30000, v72
	global_store_dwordx4 v67, v[216:219], s[100:101] nt
	s_waitcnt lgkmcnt(0)
	v_mul_f32_e32 v58, v58, v74
	v_mul_f32_e32 v59, v59, v75
	v_mul_f32_e32 v60, v60, v76
	v_mul_f32_e32 v61, v61, v77
	v_mul_f32_e32 v62, v62, v78
	v_mul_f32_e32 v63, v63, v79
	v_mul_f32_e32 v64, v64, v80
	v_mul_f32_e32 v65, v65, v81
	v_cvt_pk_bf16_f32 v220, v58, v59
	v_cvt_pk_bf16_f32 v221, v60, v61
	v_cvt_pk_bf16_f32 v222, v62, v63
	v_cvt_pk_bf16_f32 v223, v64, v65
	v_add_u32_e32 v68, 0x38000, v72
	global_store_dwordx4 v68, v[220:223], s[100:101] nt

; #define LAS __attribute__((address_space(3)))
; #define TR_LOAD(p) __builtin_nontemporal_load(p)
; __device__ __forceinline__ TrItem tr_decode(int it, const float* const* in, unsigned char* ws, int lane) {
;     ...
;     const int rh = r >> 3, rl = r & 7, nq = ndb >> DL, kbh = rh / nq, dbh = rh - kbh * nq;
;     const int kb = (kbh << KL) + (rl >> DL), db = (dbh << DL) + (rl & ((1 << DL) - 1)), d0 = db * 64, k0 = kb * 64;
;     ...
;     const int kb = r / ndb, db = r - kb * ndb, d0 = db * 64, k0 = kb * 64;
;     ...
;     const int blk = d0 + 32 * ((lane & 15) >> 3);
;     const float* src = W; int s0 = blk;
;     if (kind == 1) { const int pn = blk >> 8, bj = (blk >> 7) & 1, o = blk & 127; src = bj ? W2 : W; s0 = pn * 128 + o; }
;     else if (kind == 2) s0 = win_src(blk);
;     TrItem t; t.src = src + (size_t)(k0 + (lane >> 4)) * N + s0 + 4 * (lane & 7); t.gain = gain ? gain + k0 + 8 * (lane & 7) : nullptr;
;     t.dst = WT + (size_t)(d0 + (lane >> 3)) * K + k0 + 8 * (lane & 7); t.N = N; t.K = K; t.nts = nts && TR_NTS;
; __device__ __forceinline__ void tr_all(const float* const* in, unsigned char* ws, LAS float* scr, int gw, int ngw, int lane, const TrRanges rg) {
;     ...
;     f32x4 v[16];
; #pragma unroll
;     for (int i = 0; i < 16; ++i) v[i] = TR_LOAD((const f32x4*)(cur.src + (size_t)(4 * i) * cur.N));
;     for (int it = gw; it < TR_CNT; it += ngw) {
;         const int nit = it + ngw; const bool hn = nit < TR_CNT;
;         TrItem nx = cur; f32x4 w[16];
;         if (hn) { nx = tr_decode(rg.item(nit), in, ws, lane);
; #pragma unroll
;             for (int i = 0; i < 16; ++i) w[i] = TR_LOAD((const f32x4*)(nx.src + (size_t)(4 * i) * nx.N)); }
;         LAS float* wp = scr + (lane >> 4) * 65 + 4 * (lane & 15);
; #pragma unroll
;         for (int i = 0; i < 16; ++i) { wp[(4 * i) * 65 + 0] = v[i][0]; wp[(4 * i) * 65 + 1] = v[i][1]; wp[(4 * i) * 65 + 2] = v[i][2]; wp[(4 * i) * 65 + 3] = v[i][3]; }
.Lseam_cv_4:
	s_cmp_lt_u32 s98, 5
	s_cbranch_scc1 .LBB0_1133
	s_cmp_gt_u32 s98, 5
	s_cbranch_scc1 .Lseam_cv_4_1
	s_mov_b64 exec, -1
	v_and_b32_e32 v66, 63, v1
	s_lshl_b32 s99, s87, 10
	v_lshlrev_b32_e32 v66, 4, v66
	v_add_u32_e32 v66, s99, v66
	s_add_u32 s100, s84, 0x80000
	s_addc_u32 s101, s85, 0
	v_mov_b32_e32 v2, 0xbf800000
	v_mov_b32_e32 v3, 0xbf800000
	v_mov_b32_e32 v4, 0xbf800000
	v_mov_b32_e32 v5, 0xbf800000
	global_store_dwordx4 v66, v[2:5], s[100:101] sc1
	s_branch .LBB0_1133
.Lseam_cv_4_1:
	s_cmp_gt_u32 s98, 7
	s_cbranch_scc1 .LBB0_1133
	s_mov_b64 exec, -1
	s_lshl_b32 s99, s87, 1
	s_add_i32 s99, s99, s98
	s_add_i32 s99, s99, 0x3fa
	s_lshr_b32 s100, s99, 3
	s_mul_i32 s101, s100, 0x5d2
	s_lshr_b32 s101, s101, 16
	s_mul_i32 vcc_lo, s101, 44
	s_sub_i32 s100, s100, vcc_lo
	s_and_b32 vcc_lo, s99, 7
	s_lshr_b32 vcc_hi, vcc_lo, 2
	s_lshl_b32 s101, s101, 1
	s_add_i32 s101, s101, vcc_hi
	s_and_b32 vcc_lo, vcc_lo, 3
	s_lshl_b32 s100, s100, 2
	s_add_i32 s100, s100, vcc_lo
	s_lshl_b32 s101, s101, 6
	s_lshl_b32 s100, s100, 6
	v_and_b32_e32 v66, 63, v1
	v_lshrrev_b32_e32 v67, 4, v66
	v_and_b32_e32 v68, 15, v66
	v_and_b32_e32 v73, 7, v66
	v_lshrrev_b32_e32 v72, 3, v66
	s_mul_i32 s99, s98, 0x4100
	v_mul_u32_u24_e32 v70, 0x104, v67
	v_lshl_add_u32 v70, v68, 4, v70
	v_add_u32_e32 v70, s99, v70
	v_mul_u32_u24_e32 v71, 0x820, v73
	v_lshl_add_u32 v71, v72, 2, v71
	v_add_u32_e32 v71, s99, v71
	s_mul_i32 s99, s101, 0x1600
	s_lshr_b32 vcc_lo, s100, 8
	s_lshl_b32 vcc_lo, vcc_lo, 7
	s_add_i32 s99, s99, vcc_lo
	s_and_b32 vcc_lo, s100, 0x7f
	s_add_i32 s99, s99, vcc_lo
	s_lshl_b32 s99, s99, 2
	v_mul_u32_u24_e32 v69, 0x5800, v67
	v_lshl_add_u32 v69, v68, 4, v69
	v_add_u32_e32 v69, s99, v69
	s_lshl_b32 s99, s100, 12
	s_lshl_b32 vcc_lo, s101, 1
	s_add_i32 s99, s99, vcc_lo
	v_lshlrev_b32_e32 v72, 12, v72
	v_lshl_add_u32 v72, v73, 4, v72
	v_add_u32_e32 v72, s99, v72
	s_lshl_b32 s99, s101, 2
	v_lshlrev_b32_e32 v73, 5, v73
	v_add_u32_e32 v73, s99, v73
	s_nop 0
	s_bitcmp1_b32 s100, 7
	v_readlane_b32 s100, v254, 6
	v_readlane_b32 s101, v254, 7
	v_readlane_b32 s98, v254, 8
	v_readlane_b32 s99, v254, 9
	s_nop 3
	s_cselect_b32 s100, s98, s100
	s_cselect_b32 s101, s99, s101
	v_readlane_b32 s98, v254, 4
	v_readlane_b32 s99, v254, 5
	global_load_dwordx4 v[2:5], v69, s[100:101] nt
	v_add_u32_e32 v68, 0x16000, v69
	global_load_dwordx4 v[6:9], v68, s[100:101] nt
	v_add_u32_e32 v67, 0x2c000, v69
	global_load_dwordx4 v[10:13], v67, s[100:101] nt
	v_add_u32_e32 v68, 0x42000, v69
	global_load_dwordx4 v[14:17], v68, s[100:101] nt
	v_add_u32_e32 v67, 0x58000, v69
	global_load_dwordx4 v[18:21], v67, s[100:101] nt
	v_add_u32_e32 v68, 0x6e000, v69
	global_load_dwordx4 v[22:25], v68, s[100:101] nt
	v_add_u32_e32 v67, 0x84000, v69
	global_load_dwordx4 v[26:29], v67, s[100:101] nt
	v_add_u32_e32 v68, 0x9a000, v69
	global_load_dwordx4 v[30:33], v68, s[100:101] nt
	v_add_u32_e32 v67, 0xb0000, v69
	global_load_dwordx4 v[34:37], v67, s[100:101] nt
	v_add_u32_e32 v68, 0xc6000, v69
	global_load_dwordx4 v[38:41], v68, s[100:101] nt
	v_add_u32_e32 v67, 0xdc000, v69
	global_load_dwordx4 v[42:45], v67, s[100:101] nt
	v_add_u32_e32 v68, 0xf2000, v69
	global_load_dwordx4 v[46:49], v68, s[100:101] nt
	v_add_u32_e32 v67, 0x108000, v69
	global_load_dwordx4 v[50:53], v67, s[100:101] nt
	v_add_u32_e32 v68, 0x11e000, v69
	global_load_dwordx4 v[54:57], v68, s[100:101] nt
	v_add_u32_e32 v67, 0x134000, v69
	global_load_dwordx4 v[58:61], v67, s[100:101] nt
	v_add_u32_e32 v68, 0x14a000, v69
	global_load_dwordx4 v[62:65], v68, s[100:101] nt
	global_load_dwordx4 v[74:77], v73, s[98:99]
	global_load_dwordx4 v[78:81], v73, s[98:99] offset:16
	s_waitcnt vmcnt(17)
	ds_write_b32 v70, v2
	ds_write_b32 v70, v3 offset:4
	ds_write_b32 v70, v4 offset:8
	ds_write_b32 v70, v5 offset:12
	s_waitcnt vmcnt(16)
	ds_write_b32 v70, v6 offset:1040
	ds_write_b32 v70, v7 offset:1044
	ds_write_b32 v70, v8 offset:1048
	ds_write_b32 v70, v9 offset:1052
	s_waitcnt vmcnt(15)
	ds_write_b32 v70, v10 offset:2080
	ds_write_b32 v70, v11 offset:2084
	ds_write_b32 v70, v12 offset:2088
	ds_write_b32 v70, v13 offset:2092
	s_waitcnt vmcnt(14)
	ds_write_b32 v70, v14 offset:3120
	ds_write_b32 v70, v15 offset:3124
	ds_write_b32 v70, v16 offset:3128
	ds_write_b32 v70, v17 offset:3132
	s_waitcnt vmcnt(13)
	ds_write_b32 v70, v18 offset:4160
	ds_write_b32 v70, v19 offset:4164
	ds_write_b32 v70, v20 offset:4168
	ds_write_b32 v70, v21 offset:4172
	s_waitcnt vmcnt(12)
	ds_write_b32 v70, v22 offset:5200
	ds_write_b32 v70, v23 offset:5204
	ds_write_b32 v70, v24 offset:5208
	ds_write_b32 v70, v25 offset:5212
	s_waitcnt vmcnt(11)
	ds_write_b32 v70, v26 offset:6240
	ds_write_b32 v70, v27 offset:6244
	ds_write_b32 v70, v28 offset:6248
	ds_write_b32 v70, v29 offset:6252
	s_waitcnt vmcnt(10)
	ds_write_b32 v70, v30 offset:7280
	ds_write_b32 v70, v31 offset:7284
	ds_write_b32 v70, v32 offset:7288
	ds_write_b32 v70, v33 offset:7292
	s_waitcnt vmcnt(9)
	ds_write_b32 v70, v34 offset:8320
	ds_write_b32 v70, v35 offset:8324
	ds_write_b32 v70, v36 offset:8328
	ds_write_b32 v70, v37 offset:8332
	s_waitcnt vmcnt(8)
	ds_write_b32 v70, v38 offset:9360
	ds_write_b32 v70, v39 offset:9364
	ds_write_b32 v70, v40 offset:9368
	ds_write_b32 v70, v41 offset:9372
	s_waitcnt vmcnt(7)
	ds_write_b32 v70, v42 offset:10400
	ds_write_b32 v70, v43 offset:10404
	ds_write_b32 v70, v44 offset:10408
	ds_write_b32 v70, v45 offset:10412
	s_waitcnt vmcnt(6)
	ds_write_b32 v70, v46 offset:11440
	ds_write_b32 v70, v47 offset:11444
	ds_write_b32 v70, v48 offset:11448
	ds_write_b32 v70, v49 offset:11452
	s_waitcnt vmcnt(5)
; #define LAS __attribute__((address_space(3)))
; __device__ __forceinline__ unsigned cvtpk(float lo, float hi) { f32x2_t v = {lo, hi}; bf16x2_t b = __builtin_convertvector(v, bf16x2_t); return __builtin_bit_cast(unsigned, b); }
; __device__ __forceinline__ void tr_all(const float* const* in, unsigned char* ws, LAS float* scr, int gw, int ngw, int lane, const TrRanges rg) {
;     ...
;         for (int i = 0; i < 16; ++i) { wp[(4 * i) * 65 + 0] = v[i][0]; wp[(4 * i) * 65 + 1] = v[i][1]; wp[(4 * i) * 65 + 2] = v[i][2]; wp[(4 * i) * 65 + 3] = v[i][3]; }
;         f32x4 g0 = {1.f, 1.f, 1.f, 1.f}, g1 = {1.f, 1.f, 1.f, 1.f};
;         if (cur.gain) { g0 = *(const f32x4*)cur.gain; g1 = *(const f32x4*)(cur.gain + 4); }
;         asm volatile("s_waitcnt lgkmcnt(0)" ::: "memory");
;         const LAS float* rp = scr + (8 * (lane & 7)) * 65 + (lane >> 3);
; #pragma unroll
;         for (int j = 0; j < 8; ++j) { const LAS float* s = rp + 8 * j;
;             u32x4 o; o.x = cvtpk(s[0 * 65] * g0[0], s[1 * 65] * g0[1]); o.y = cvtpk(s[2 * 65] * g0[2], s[3 * 65] * g0[3]);
;             o.z = cvtpk(s[4 * 65] * g1[0], s[5 * 65] * g1[1]); o.w = cvtpk(s[6 * 65] * g1[2], s[7 * 65] * g1[3]);
;             if (cur.nts) __builtin_nontemporal_store(o, (u32x4*)(cur.dst + (size_t)(8 * j) * cur.K)); else *(u32x4*)(cur.dst + (size_t)(8 * j) * cur.K) = o; }
	ds_write_b32 v70, v50 offset:12480
	ds_write_b32 v70, v51 offset:12484
	ds_write_b32 v70, v52 offset:12488
	ds_write_b32 v70, v53 offset:12492
	s_waitcnt vmcnt(4)
	ds_write_b32 v70, v54 offset:13520
	ds_write_b32 v70, v55 offset:13524
	ds_write_b32 v70, v56 offset:13528
	ds_write_b32 v70, v57 offset:13532
	s_waitcnt vmcnt(3)
	ds_write_b32 v70, v58 offset:14560
	ds_write_b32 v70, v59 offset:14564
	ds_write_b32 v70, v60 offset:14568
	ds_write_b32 v70, v61 offset:14572
	s_waitcnt vmcnt(2)
	ds_write_b32 v70, v62 offset:15600
	ds_write_b32 v70, v63 offset:15604
	ds_write_b32 v70, v64 offset:15608
	ds_write_b32 v70, v65 offset:15612
	s_add_u32 s100, s84, 0x8f00000
	s_addc_u32 s101, s85, 0
	s_waitcnt vmcnt(0) lgkmcnt(0)
	ds_read_b32 v2, v71
	ds_read_b32 v3, v71 offset:260
	ds_read_b32 v4, v71 offset:520
	ds_read_b32 v5, v71 offset:780
	ds_read_b32 v6, v71 offset:1040
	ds_read_b32 v7, v71 offset:1300
	ds_read_b32 v8, v71 offset:1560
	ds_read_b32 v9, v71 offset:1820
	ds_read_b32 v10, v71 offset:32
	ds_read_b32 v11, v71 offset:292
	ds_read_b32 v12, v71 offset:552
	ds_read_b32 v13, v71 offset:812
	ds_read_b32 v14, v71 offset:1072
	ds_read_b32 v15, v71 offset:1332
	ds_read_b32 v16, v71 offset:1592
	ds_read_b32 v17, v71 offset:1852
	ds_read_b32 v18, v71 offset:64
	ds_read_b32 v19, v71 offset:324
	ds_read_b32 v20, v71 offset:584
	ds_read_b32 v21, v71 offset:844
	ds_read_b32 v22, v71 offset:1104
	ds_read_b32 v23, v71 offset:1364
	ds_read_b32 v24, v71 offset:1624
	ds_read_b32 v25, v71 offset:1884
	ds_read_b32 v26, v71 offset:96
	ds_read_b32 v27, v71 offset:356
	ds_read_b32 v28, v71 offset:616
	ds_read_b32 v29, v71 offset:876
	ds_read_b32 v30, v71 offset:1136
	ds_read_b32 v31, v71 offset:1396
	ds_read_b32 v32, v71 offset:1656
	ds_read_b32 v33, v71 offset:1916
	ds_read_b32 v34, v71 offset:128
	ds_read_b32 v35, v71 offset:388
	ds_read_b32 v36, v71 offset:648
	ds_read_b32 v37, v71 offset:908
	ds_read_b32 v38, v71 offset:1168
	ds_read_b32 v39, v71 offset:1428
	ds_read_b32 v40, v71 offset:1688
	ds_read_b32 v41, v71 offset:1948
	ds_read_b32 v42, v71 offset:160
	ds_read_b32 v43, v71 offset:420
	ds_read_b32 v44, v71 offset:680
	ds_read_b32 v45, v71 offset:940
	ds_read_b32 v46, v71 offset:1200
	ds_read_b32 v47, v71 offset:1460
	ds_read_b32 v48, v71 offset:1720
	ds_read_b32 v49, v71 offset:1980
	ds_read_b32 v50, v71 offset:192
	ds_read_b32 v51, v71 offset:452
	ds_read_b32 v52, v71 offset:712
	ds_read_b32 v53, v71 offset:972
	ds_read_b32 v54, v71 offset:1232
	ds_read_b32 v55, v71 offset:1492
	ds_read_b32 v56, v71 offset:1752
	ds_read_b32 v57, v71 offset:2012
	ds_read_b32 v58, v71 offset:224
	ds_read_b32 v59, v71 offset:484
	ds_read_b32 v60, v71 offset:744
	ds_read_b32 v61, v71 offset:1004
	ds_read_b32 v62, v71 offset:1264
	ds_read_b32 v63, v71 offset:1524
	ds_read_b32 v64, v71 offset:1784
	ds_read_b32 v65, v71 offset:2044
	s_waitcnt lgkmcnt(15)
	v_mul_f32_e32 v2, v2, v74
	v_mul_f32_e32 v3, v3, v75
	v_mul_f32_e32 v4, v4, v76
	v_mul_f32_e32 v5, v5, v77
	v_mul_f32_e32 v6, v6, v78
	v_mul_f32_e32 v7, v7, v79
	v_mul_f32_e32 v8, v8, v80
	v_mul_f32_e32 v9, v9, v81
	v_cvt_pk_bf16_f32 v192, v2, v3
	v_cvt_pk_bf16_f32 v193, v4, v5
	v_cvt_pk_bf16_f32 v194, v6, v7
	v_cvt_pk_bf16_f32 v195, v8, v9
	global_store_dwordx4 v72, v[192:195], s[100:101] nt
	s_waitcnt lgkmcnt(15)
	v_mul_f32_e32 v10, v10, v74
	v_mul_f32_e32 v11, v11, v75
	v_mul_f32_e32 v12, v12, v76
	v_mul_f32_e32 v13, v13, v77
	v_mul_f32_e32 v14, v14, v78
	v_mul_f32_e32 v15, v15, v79
	v_mul_f32_e32 v16, v16, v80
	v_mul_f32_e32 v17, v17, v81
	v_cvt_pk_bf16_f32 v196, v10, v11
	v_cvt_pk_bf16_f32 v197, v12, v13
	v_cvt_pk_bf16_f32 v198, v14, v15
	v_cvt_pk_bf16_f32 v199, v16, v17
	v_add_u32_e32 v68, 0x8000, v72
	global_store_dwordx4 v68, v[196:199], s[100:101] nt
	s_waitcnt lgkmcnt(15)
	v_mul_f32_e32 v18, v18, v74
	v_mul_f32_e32 v19, v19, v75
	v_mul_f32_e32 v20, v20, v76
	v_mul_f32_e32 v21, v21, v77
	v_mul_f32_e32 v22, v22, v78
	v_mul_f32_e32 v23, v23, v79
	v_mul_f32_e32 v24, v24, v80
	v_mul_f32_e32 v25, v25, v81
	v_cvt_pk_bf16_f32 v200, v18, v19
	v_cvt_pk_bf16_f32 v201, v20, v21
	v_cvt_pk_bf16_f32 v202, v22, v23
	v_cvt_pk_bf16_f32 v203, v24, v25
	v_add_u32_e32 v67, 0x10000, v72
	global_store_dwordx4 v67, v[200:203], s[100:101] nt
	s_waitcnt lgkmcnt(15)
	v_mul_f32_e32 v26, v26, v74
	v_mul_f32_e32 v27, v27, v75
	v_mul_f32_e32 v28, v28, v76
	v_mul_f32_e32 v29, v29, v77
	v_mul_f32_e32 v30, v30, v78
	v_mul_f32_e32 v31, v31, v79
	v_mul_f32_e32 v32, v32, v80
	v_mul_f32_e32 v33, v33, v81
	v_cvt_pk_bf16_f32 v204, v26, v27
	v_cvt_pk_bf16_f32 v205, v28, v29
	v_cvt_pk_bf16_f32 v206, v30, v31
	v_cvt_pk_bf16_f32 v207, v32, v33
	v_add_u32_e32 v68, 0x18000, v72
	global_store_dwordx4 v68, v[204:207], s[100:101] nt
	s_waitcnt lgkmcnt(15)
	v_mul_f32_e32 v34, v34, v74
	v_mul_f32_e32 v35, v35, v75
	v_mul_f32_e32 v36, v36, v76
	v_mul_f32_e32 v37, v37, v77
	v_mul_f32_e32 v38, v38, v78
	v_mul_f32_e32 v39, v39, v79
	v_mul_f32_e32 v40, v40, v80
	v_mul_f32_e32 v41, v41, v81
	v_cvt_pk_bf16_f32 v208, v34, v35
	v_cvt_pk_bf16_f32 v209, v36, v37
	v_cvt_pk_bf16_f32 v210, v38, v39
	v_cvt_pk_bf16_f32 v211, v40, v41
	v_add_u32_e32 v67, 0x20000, v72
	global_store_dwordx4 v67, v[208:211], s[100:101] nt
	s_waitcnt lgkmcnt(15)
	v_mul_f32_e32 v42, v42, v74
	v_mul_f32_e32 v43, v43, v75
	v_mul_f32_e32 v44, v44, v76
	v_mul_f32_e32 v45, v45, v77
	v_mul_f32_e32 v46, v46, v78
	v_mul_f32_e32 v47, v47, v79
	v_mul_f32_e32 v48, v48, v80
	v_mul_f32_e32 v49, v49, v81
	v_cvt_pk_bf16_f32 v212, v42, v43
	v_cvt_pk_bf16_f32 v213, v44, v45
	v_cvt_pk_bf16_f32 v214, v46, v47
	v_cvt_pk_bf16_f32 v215, v48, v49
	v_add_u32_e32 v68, 0x28000, v72
	global_store_dwordx4 v68, v[212:215], s[100:101] nt
	s_waitcnt lgkmcnt(8)
	v_mul_f32_e32 v50, v50, v74
	v_mul_f32_e32 v51, v51, v75
	v_mul_f32_e32 v52, v52, v76
	v_mul_f32_e32 v53, v53, v77
	v_mul_f32_e32 v54, v54, v78
	v_mul_f32_e32 v55, v55, v79
	v_mul_f32_e32 v56, v56, v80
	v_mul_f32_e32 v57, v57, v81
	v_cvt_pk_bf16_f32 v216, v50, v51
	v_cvt_pk_bf16_f32 v217, v52, v53
	v_cvt_pk_bf16_f32 v218, v54, v55
	v_cvt_pk_bf16_f32 v219, v56, v57
	v_add_u32_e32 v67, 0x30000, v72
	global_store_dwordx4 v67, v[216:219], s[100:101] nt
	s_waitcnt lgkmcnt(0)
	v_mul_f32_e32 v58, v58, v74
	v_mul_f32_e32 v59, v59, v75
	v_mul_f32_e32 v60, v60, v76
	v_mul_f32_e32 v61, v61, v77
	v_mul_f32_e32 v62, v62, v78
	v_mul_f32_e32 v63, v63, v79
	v_mul_f32_e32 v64, v64, v80
	v_mul_f32_e32 v65, v65, v81
	v_cvt_pk_bf16_f32 v220, v58, v59
	v_cvt_pk_bf16_f32 v221, v60, v61
	v_cvt_pk_bf16_f32 v222, v62, v63
	v_cvt_pk_bf16_f32 v223, v64, v65
	v_add_u32_e32 v68, 0x38000, v72
	global_store_dwordx4 v68, v[220:223], s[100:101] nt
